# deferred weight conversion, early start: a converting wave issues its item's loads before the grid-barrier arrival (waits vmcnt(16) for its own phase stores), finishes the item during the barrier; 640
# baseline (speedup 1.0000x reference)
; #define LAS __attribute__((address_space(3)))
; #define LDS_WAIT() asm volatile("s_waitcnt lgkmcnt(0)" ::: "memory")
; __device__ __forceinline__ unsigned pk2(float lo, float hi) { return pg8::cvt_pk_bf16(lo, hi); }
; __device__ __forceinline__ void xpose_item(const float* W, int K, int N, bf16* WT, const float* gain, int cmap, LAS float* scr, int item, int lane) {
;     ...
;     for (int i = 0; i < 16; ++i) w[i] = __builtin_nontemporal_load((const f32x4*)(W + (size_t)(k0 + 4 * i + ks) * N + n0 + n4));
;     if (gain) {
; #pragma unroll
;         for (int i = 0; i < 16; ++i) w[i] = w[i] * gain[k0 + 4 * i + ks];
;     }
; #pragma unroll
;     for (int i = 0; i < 16; ++i) { LAS float* d = scr + (4 * i + ks) * XP_STRIDE + n4; d[0] = w[i][0]; d[1] = w[i][1]; d[2] = w[i][2]; d[3] = w[i][3]; }
;     LDS_WAIT(); asm volatile("" ::: "memory");
;     int r0 = n0;
;     if (cmap == 1) { if (n0 < 1024) r0 = 2048 + n0; else if (n0 < 2048) { const int c = n0 - 1024; r0 = (c >> 7) * 256 + (c & 127); } else { const int c = n0 - 2048; r0 = (c >> 7) * 256 + 128 + (c & 127); } }
;     const int c = lane & 7;
; #pragma unroll
;     for (int j = 0; j < 8; ++j) { const int n = (lane >> 3) + 8 * j; const LAS float* sp = scr + (8 * c) * XP_STRIDE + n;
;         v4u o; o.x = pk2(sp[0 * XP_STRIDE], sp[1 * XP_STRIDE]); o.y = pk2(sp[2 * XP_STRIDE], sp[3 * XP_STRIDE]); o.z = pk2(sp[4 * XP_STRIDE], sp[5 * XP_STRIDE]); o.w = pk2(sp[6 * XP_STRIDE], sp[7 * XP_STRIDE]);
;         int rr = r0 + n;
;         if (cmap == 4) { const int cc = rr & 255; rr = (rr & ~255) + 128 * ((cc >> 5) & 1) + 32 * (cc >> 6) + (cc & 31); }
;         *(v4u*)(WT + (size_t)rr * K + k0 + 8 * c) = o; }
;     LDS_WAIT(); asm volatile("" ::: "memory");
.LBB0_527:
	s_cselect_b32 s84, 1, 0
	s_cmp_eq_u32 s32, 1
	s_cbranch_scc1 .Lmy_yield_0
.Lmy_resume_0:
	s_cmp_lg_u32 s84, 0
	s_waitcnt vmcnt(15)
	ds_write2_b32 v69, v62, v63 offset1:1
	ds_write2_b32 v69, v64, v65 offset0:2 offset1:3
	v_add_u32_e32 v62, 0x410, v69
	s_waitcnt vmcnt(14)
	ds_write2_b32 v62, v50, v51 offset1:1
	v_add_u32_e32 v50, 0x418, v69
	ds_write2_b32 v50, v52, v53 offset1:1
	v_add_u32_e32 v50, 0x820, v69
	s_waitcnt vmcnt(13)
	ds_write2_b32 v50, v58, v59 offset1:1
	v_add_u32_e32 v50, 0x828, v69
	ds_write2_b32 v50, v60, v61 offset1:1
	v_add_u32_e32 v50, 0xc30, v69
	s_waitcnt vmcnt(12)
	ds_write2_b32 v50, v42, v43 offset1:1
	v_add_u32_e32 v42, 0xc38, v69
	ds_write2_b32 v42, v44, v45 offset1:1
	v_add_u32_e32 v42, 0x1040, v69
	s_waitcnt vmcnt(11)
	ds_write2_b32 v42, v54, v55 offset1:1
	v_add_u32_e32 v42, 0x1048, v69
	ds_write2_b32 v42, v56, v57 offset1:1
	v_add_u32_e32 v42, 0x1450, v69
	s_waitcnt vmcnt(10)
	ds_write2_b32 v42, v34, v35 offset1:1
	v_add_u32_e32 v34, 0x1458, v69
	ds_write2_b32 v34, v36, v37 offset1:1
	v_add_u32_e32 v34, 0x1860, v69
	s_waitcnt vmcnt(9)
	ds_write2_b32 v34, v46, v47 offset1:1
	v_add_u32_e32 v34, 0x1868, v69
	ds_write2_b32 v34, v48, v49 offset1:1
	v_add_u32_e32 v34, 0x1c70, v69
	s_waitcnt vmcnt(8)
	ds_write2_b32 v34, v26, v27 offset1:1
	v_add_u32_e32 v26, 0x1c78, v69
	ds_write2_b32 v26, v28, v29 offset1:1
	v_add_u32_e32 v26, 0x2080, v69
	s_waitcnt vmcnt(7)
	ds_write2_b32 v26, v38, v39 offset1:1
	v_add_u32_e32 v26, 0x2088, v69
	ds_write2_b32 v26, v40, v41 offset1:1
	v_add_u32_e32 v26, 0x2490, v69
	s_waitcnt vmcnt(6)
	ds_write2_b32 v26, v18, v19 offset1:1
	v_add_u32_e32 v18, 0x2498, v69
	ds_write2_b32 v18, v20, v21 offset1:1
	v_add_u32_e32 v18, 0x28a0, v69
	s_waitcnt vmcnt(5)
	ds_write2_b32 v18, v30, v31 offset1:1
	v_add_u32_e32 v18, 0x28a8, v69
	ds_write2_b32 v18, v32, v33 offset1:1
	v_add_u32_e32 v18, 0x2cb0, v69
	s_waitcnt vmcnt(4)
	ds_write2_b32 v18, v10, v11 offset1:1
	v_add_u32_e32 v10, 0x2cb8, v69
	ds_write2_b32 v10, v12, v13 offset1:1
	v_add_u32_e32 v10, 0x30c0, v69
	s_waitcnt vmcnt(3)
	ds_write2_b32 v10, v22, v23 offset1:1
	v_add_u32_e32 v10, 0x30c8, v69
	ds_write2_b32 v10, v24, v25 offset1:1
	v_add_u32_e32 v10, 0x34d0, v69
	s_waitcnt vmcnt(2)
	ds_write2_b32 v10, v6, v7 offset1:1
	v_add_u32_e32 v6, 0x34d8, v69
	ds_write2_b32 v6, v8, v9 offset1:1
	v_add_u32_e32 v6, 0x38e0, v69
	s_waitcnt vmcnt(1)
	ds_write2_b32 v6, v14, v15 offset1:1
	v_add_u32_e32 v6, 0x38e8, v69
	ds_write2_b32 v6, v16, v17 offset1:1
	v_add_u32_e32 v6, 0x3cf0, v69
	s_mul_hi_i32 s3, s2, 0x600000
	s_mul_i32 s2, s2, 0x600000
	v_readlane_b32 s5, v253, 16
	s_waitcnt vmcnt(0)
	ds_write2_b32 v6, v2, v3 offset1:1
	v_add_u32_e32 v2, 0x3cf8, v69
	s_add_u32 s5, s5, s2
	v_readlane_b32 s2, v253, 17
	ds_write2_b32 v2, v4, v5 offset1:1
	s_addc_u32 s8, s2, s3
	s_ashr_i32 s11, s10, 31
	s_waitcnt lgkmcnt(0)
	s_lshl_b64 s[2:3], s[10:11], 1
	s_add_u32 s2, s5, s2
	ds_read2_b32 v[2:3], v73 offset1:65
	s_addc_u32 s3, s8, s3
	v_lshlrev_b32_e32 v98, 1, v72
	s_waitcnt lgkmcnt(0)
	v_cvt_pk_bf16_f32 v2, v2, v3
	ds_read2_b32 v[4:5], v73 offset0:130 offset1:195
	v_add_u32_e32 v14, 0x400, v73
	v_lshl_add_u64 v[8:9], s[2:3], 0, v[98:99]
	s_lshr_b32 s2, s4, 1
	s_waitcnt lgkmcnt(0)
	v_cvt_pk_bf16_f32 v3, v4, v5
	ds_read2_b32 v[4:5], v14 offset0:4 offset1:69
	s_and_b32 s2, s2, 0x60
	s_and_b32 s3, s4, 0xffffff00
	s_waitcnt lgkmcnt(0)
	v_cvt_pk_bf16_f32 v4, v4, v5
	ds_read2_b32 v[6:7], v14 offset0:134 offset1:199
	s_or_b32 s3, s2, s3
	s_waitcnt lgkmcnt(0)
	v_cvt_pk_bf16_f32 v5, v6, v7
	v_or_b32_e32 v6, s3, v71
	v_ashrrev_i32_e32 v7, 31, v6
	v_lshlrev_b64 v[12:13], 11, v[6:7]
	v_lshl_add_u64 v[12:13], v[8:9], 0, v[12:13]
	ds_read2_b32 v[10:11], v73 offset0:8 offset1:73
	global_store_dwordx4 v[12:13], v[2:5], off sc1
	v_or_b32_e32 v6, 0x80, v6
	v_ashrrev_i32_e32 v7, 31, v6
	s_waitcnt lgkmcnt(0)
	v_cvt_pk_bf16_f32 v2, v10, v11
	ds_read2_b32 v[4:5], v73 offset0:138 offset1:203
	s_waitcnt lgkmcnt(0)
	v_cvt_pk_bf16_f32 v3, v4, v5
	ds_read2_b32 v[4:5], v14 offset0:12 offset1:77
	s_waitcnt lgkmcnt(0)
	v_cvt_pk_bf16_f32 v4, v4, v5
	ds_read2_b32 v[10:11], v14 offset0:142 offset1:207
	s_waitcnt lgkmcnt(0)
; #define LAS __attribute__((address_space(3)))
; #define LDS_WAIT() asm volatile("s_waitcnt lgkmcnt(0)" ::: "memory")
; __device__ __forceinline__ unsigned pk2(float lo, float hi) { return pg8::cvt_pk_bf16(lo, hi); }
; __device__ __forceinline__ void xpose_item(const float* W, int K, int N, bf16* WT, const float* gain, int cmap, LAS float* scr, int item, int lane) {
;     ...
;     const int c = lane & 7;
; #pragma unroll
;     for (int j = 0; j < 8; ++j) { const int n = (lane >> 3) + 8 * j; const LAS float* sp = scr + (8 * c) * XP_STRIDE + n;
;         v4u o; o.x = pk2(sp[0 * XP_STRIDE], sp[1 * XP_STRIDE]); o.y = pk2(sp[2 * XP_STRIDE], sp[3 * XP_STRIDE]); o.z = pk2(sp[4 * XP_STRIDE], sp[5 * XP_STRIDE]); o.w = pk2(sp[6 * XP_STRIDE], sp[7 * XP_STRIDE]);
;         int rr = r0 + n;
;         if (cmap == 4) { const int cc = rr & 255; rr = (rr & ~255) + 128 * ((cc >> 5) & 1) + 32 * (cc >> 6) + (cc & 31); }
;         *(v4u*)(WT + (size_t)rr * K + k0 + 8 * c) = o; }
;     LDS_WAIT(); asm volatile("" ::: "memory");
	v_cvt_pk_bf16_f32 v5, v10, v11
	v_or_b32_e32 v10, s3, v84
	v_ashrrev_i32_e32 v11, 31, v10
	v_lshlrev_b64 v[10:11], 11, v[10:11]
	v_lshl_add_u64 v[10:11], v[8:9], 0, v[10:11]
	ds_read2_b32 v[12:13], v73 offset0:16 offset1:81
	global_store_dwordx4 v[10:11], v[2:5], off sc1
	v_lshlrev_b64 v[6:7], 11, v[6:7]
	v_lshl_add_u64 v[6:7], v[8:9], 0, v[6:7]
	s_waitcnt lgkmcnt(0)
	v_cvt_pk_bf16_f32 v2, v12, v13
	ds_read2_b32 v[4:5], v73 offset0:146 offset1:211
	s_waitcnt lgkmcnt(0)
	v_cvt_pk_bf16_f32 v3, v4, v5
	ds_read2_b32 v[4:5], v14 offset0:20 offset1:85
	s_waitcnt lgkmcnt(0)
	v_cvt_pk_bf16_f32 v4, v4, v5
	ds_read2_b32 v[10:11], v14 offset0:150 offset1:215
	s_waitcnt lgkmcnt(0)
	v_cvt_pk_bf16_f32 v5, v10, v11
	v_or_b32_e32 v10, s3, v85
	v_ashrrev_i32_e32 v11, 31, v10
	v_lshlrev_b64 v[10:11], 11, v[10:11]
	v_lshl_add_u64 v[10:11], v[8:9], 0, v[10:11]
	ds_read2_b32 v[12:13], v73 offset0:24 offset1:89
	global_store_dwordx4 v[10:11], v[2:5], off sc1
	s_waitcnt lgkmcnt(0)
	s_nop 0
	v_cvt_pk_bf16_f32 v2, v12, v13
	ds_read2_b32 v[4:5], v73 offset0:154 offset1:219
	s_waitcnt lgkmcnt(0)
	v_cvt_pk_bf16_f32 v3, v4, v5
	ds_read2_b32 v[4:5], v14 offset0:28 offset1:93
	s_waitcnt lgkmcnt(0)
	v_cvt_pk_bf16_f32 v4, v4, v5
	ds_read2_b32 v[10:11], v14 offset0:158 offset1:223
	s_waitcnt lgkmcnt(0)
	v_cvt_pk_bf16_f32 v5, v10, v11
	v_or_b32_e32 v10, s3, v86
	v_ashrrev_i32_e32 v11, 31, v10
	v_lshlrev_b64 v[10:11], 11, v[10:11]
	v_lshl_add_u64 v[10:11], v[8:9], 0, v[10:11]
	ds_read2_b32 v[12:13], v73 offset0:32 offset1:97
	global_store_dwordx4 v[10:11], v[2:5], off sc1
	s_waitcnt lgkmcnt(0)
	s_nop 0
	v_cvt_pk_bf16_f32 v2, v12, v13
	ds_read2_b32 v[4:5], v73 offset0:162 offset1:227
	s_waitcnt lgkmcnt(0)
	v_cvt_pk_bf16_f32 v3, v4, v5
	ds_read2_b32 v[4:5], v14 offset0:36 offset1:101
	s_waitcnt lgkmcnt(0)
	v_cvt_pk_bf16_f32 v4, v4, v5
	ds_read2_b32 v[10:11], v14 offset0:166 offset1:231
	s_waitcnt lgkmcnt(0)
	v_cvt_pk_bf16_f32 v5, v10, v11
	ds_read2_b32 v[10:11], v73 offset0:40 offset1:105
	global_store_dwordx4 v[6:7], v[2:5], off sc1
	s_waitcnt lgkmcnt(0)
	s_nop 0
	v_cvt_pk_bf16_f32 v2, v10, v11
	ds_read2_b32 v[4:5], v73 offset0:170 offset1:235
	s_waitcnt lgkmcnt(0)
	v_cvt_pk_bf16_f32 v3, v4, v5
	ds_read2_b32 v[4:5], v14 offset0:44 offset1:109
	s_waitcnt lgkmcnt(0)
	v_cvt_pk_bf16_f32 v4, v4, v5
	ds_read2_b32 v[6:7], v14 offset0:174 offset1:239
	s_waitcnt lgkmcnt(0)
	v_cvt_pk_bf16_f32 v5, v6, v7
	v_mov_b32_e32 v6, 0xffffff0f
	v_bitop3_b32 v6, s4, v6, v87 bitop3:0xc8
	v_or_b32_e32 v6, s2, v6
	v_or_b32_e32 v6, 0x80, v6
	v_ashrrev_i32_e32 v7, 31, v6
	v_lshlrev_b64 v[6:7], 11, v[6:7]
	v_lshl_add_u64 v[6:7], v[8:9], 0, v[6:7]
	ds_read2_b32 v[10:11], v73 offset0:48 offset1:113
	global_store_dwordx4 v[6:7], v[2:5], off sc1
	s_waitcnt lgkmcnt(0)
	s_nop 0
	v_cvt_pk_bf16_f32 v2, v10, v11
	ds_read2_b32 v[4:5], v73 offset0:178 offset1:243
	s_waitcnt lgkmcnt(0)
	v_cvt_pk_bf16_f32 v3, v4, v5
	ds_read2_b32 v[4:5], v14 offset0:52 offset1:117
	s_waitcnt lgkmcnt(0)
	v_cvt_pk_bf16_f32 v4, v4, v5
	ds_read2_b32 v[6:7], v14 offset0:182 offset1:247
	s_waitcnt lgkmcnt(0)
	v_cvt_pk_bf16_f32 v5, v6, v7
	v_mov_b32_e32 v6, 0xffffff17
	v_bitop3_b32 v6, s4, v6, v88 bitop3:0xc8
	v_or_b32_e32 v6, s2, v6
	v_or_b32_e32 v6, 0x80, v6
	v_ashrrev_i32_e32 v7, 31, v6
	v_lshlrev_b64 v[6:7], 11, v[6:7]
	v_lshl_add_u64 v[6:7], v[8:9], 0, v[6:7]
	ds_read2_b32 v[10:11], v73 offset0:56 offset1:121
	global_store_dwordx4 v[6:7], v[2:5], off sc1
	s_waitcnt lgkmcnt(0)
	s_nop 0
	v_cvt_pk_bf16_f32 v2, v10, v11
	ds_read2_b32 v[4:5], v73 offset0:186 offset1:251
	s_waitcnt lgkmcnt(0)
	v_cvt_pk_bf16_f32 v3, v4, v5
	ds_read2_b32 v[4:5], v14 offset0:60 offset1:125
	s_waitcnt lgkmcnt(0)
	v_cvt_pk_bf16_f32 v4, v4, v5
	ds_read2_b32 v[6:7], v14 offset0:190 offset1:255
	s_waitcnt lgkmcnt(0)
	v_cvt_pk_bf16_f32 v5, v6, v7
	v_mov_b32_e32 v6, 0xffffff1f
	v_bitop3_b32 v6, s4, v6, v89 bitop3:0xc8
	v_or_b32_e32 v6, s2, v6
	v_or_b32_e32 v6, 0x80, v6
	v_ashrrev_i32_e32 v7, 31, v6
	v_lshlrev_b64 v[6:7], 11, v[6:7]
	v_lshl_add_u64 v[6:7], v[8:9], 0, v[6:7]
	global_store_dwordx4 v[6:7], v[2:5], off sc1
	s_waitcnt lgkmcnt(0)

; #define LAS __attribute__((address_space(3)))
; __device__ __forceinline__ void xpose_item(const float* W, int K, int N, bf16* WT, const float* gain, int cmap, LAS float* scr, int item, int lane) {
;     const int nblk = N / 64, kb = item / nblk, nb = item % nblk, k0 = 64 * kb, n0 = 64 * nb;
;     const int n4 = (lane & 15) * 4, ks = lane >> 4;
;     f32x4 w[16];
; #pragma unroll
;     for (int i = 0; i < 16; ++i) w[i] = __builtin_nontemporal_load((const f32x4*)(W + (size_t)(k0 + 4 * i + ks) * N + n0 + n4));
;     if (gain) {
; #pragma unroll
;         for (int i = 0; i < 16; ++i) w[i] = w[i] * gain[k0 + 4 * i + ks];
;     }
; #pragma unroll
;     for (int i = 0; i < 16; ++i) { LAS float* d = scr + (4 * i + ks) * XP_STRIDE + n4; d[0] = w[i][0]; d[1] = w[i][1]; d[2] = w[i][2]; d[3] = w[i][3]; }
; __device__ __forceinline__ void prologue(const Args& a, LAS unsigned char* lds, int vcu, int G, int wave, int lane, int tid) {
;     ...
;         if (r < 4 * I_UP) { const int l = r / I_UP; r -= l * I_UP; xpose_item(a.in[11] + (size_t)l * 1024 * 4096, 1024, 4096, (bf16*)(ws + WS_WUP) + (size_t)l * 4096 * 1024, nmlp + l * 1024, 4, scr, r, lane); continue; } r -= 4 * I_UP;
;         { const int l = r / I_DN; r -= l * I_DN; xpose_item(a.in[12] + (size_t)l * 4096 * 1024, 4096, 1024, (bf16*)(ws + WS_WDN) + (size_t)l * 1024 * 4096, nullptr, 4, scr, r, lane); }
.LBB0_529:
	s_add_i32 s2, s7, 0x1c40
	s_cmpk_gt_i32 s2, 0x5ff
	s_mov_b64 s[4:5], -1
	s_cbranch_scc0 .LBB0_561
	s_cmpk_gt_u32 s2, 0x7ff
	s_cbranch_scc0 .LBB0_558
	s_cmpk_gt_u32 s2, 0x83f
	s_cbranch_scc0 .LBB0_555
	s_cmpk_gt_u32 s2, 0xb3f
	s_cbranch_scc0 .LBB0_544
	s_cmpk_gt_u32 s2, 0xc3f
	s_cbranch_scc0 .LBB0_541
	s_cmpk_gt_u32 s2, 0x1c3f
	s_cbranch_scc0 .LBB0_536
	s_lshr_b32 s86, s7, 10
	s_lshl_b64 s[4:5], s[86:87], 24
	s_add_u32 s3, s56, s4
	s_addc_u32 s8, s57, s5
	s_lshl_b64 s[4:5], s[86:87], 23
	v_readlane_b32 s9, v253, 3
	s_add_u32 s9, s9, s4
	v_readlane_b32 s4, v253, 4
	s_addc_u32 s10, s4, s5
	s_add_i32 s4, s1, 0xffff8f00
	s_and_b32 s11, s4, 0xfc0
	s_and_b32 s4, s13, 0x3c0
	s_lshl_b32 s4, s4, 2
	s_add_u32 s4, s3, s4
	v_or_b32_e32 v4, s11, v67
	s_addc_u32 s5, s8, 0
	v_lshlrev_b32_e32 v98, 2, v70
	v_lshl_add_u64 v[2:3], s[4:5], 0, v[98:99]
	v_lshlrev_b32_e32 v98, 12, v4
	v_lshl_add_u64 v[62:63], v[2:3], 0, v[98:99]
	s_movk_i32 s3, 0x4000
	v_add_co_u32_e32 v6, vcc, s3, v62
	s_mov_b32 s3, 0x8000
	s_nop 0
	v_addc_co_u32_e32 v7, vcc, 0, v63, vcc
	v_add_co_u32_e32 v10, vcc, s3, v62
	global_load_dwordx4 v[2:5], v[62:63], off nt
	s_nop 0
	global_load_dwordx4 v[6:9], v[6:7], off nt
	v_addc_co_u32_e32 v11, vcc, 0, v63, vcc
	s_mov_b32 s3, 0xc000
	v_add_co_u32_e32 v14, vcc, s3, v62
	s_mov_b32 s3, 0x10000
	s_nop 0
	v_addc_co_u32_e32 v15, vcc, 0, v63, vcc
	global_load_dwordx4 v[10:13], v[10:11], off nt
	s_nop 0
	global_load_dwordx4 v[14:17], v[14:15], off nt
	v_add_co_u32_e32 v18, vcc, s3, v62
	s_mov_b32 s3, 0x14000
	s_nop 0
	v_addc_co_u32_e32 v19, vcc, 0, v63, vcc
	v_add_co_u32_e32 v22, vcc, s3, v62
	s_mov_b32 s3, 0x18000
	s_nop 0
	v_addc_co_u32_e32 v23, vcc, 0, v63, vcc
	global_load_dwordx4 v[18:21], v[18:19], off nt
	s_nop 0
	global_load_dwordx4 v[22:25], v[22:23], off nt
	v_add_co_u32_e32 v26, vcc, s3, v62
	s_mov_b32 s3, 0x1c000
	s_nop 0
	v_addc_co_u32_e32 v27, vcc, 0, v63, vcc
	v_add_co_u32_e32 v30, vcc, s3, v62
	s_mov_b32 s3, 0x20000
	s_nop 0
	v_addc_co_u32_e32 v31, vcc, 0, v63, vcc
	global_load_dwordx4 v[26:29], v[26:27], off nt
	s_nop 0
	global_load_dwordx4 v[30:33], v[30:31], off nt
	v_add_co_u32_e32 v34, vcc, s3, v62
	s_mov_b32 s3, 0x24000
	s_nop 0
	v_addc_co_u32_e32 v35, vcc, 0, v63, vcc
	v_add_co_u32_e32 v38, vcc, s3, v62
	s_mov_b32 s3, 0x28000
	s_nop 0
	v_addc_co_u32_e32 v39, vcc, 0, v63, vcc
	global_load_dwordx4 v[34:37], v[34:35], off nt
	s_nop 0
	global_load_dwordx4 v[38:41], v[38:39], off nt
	v_add_co_u32_e32 v42, vcc, s3, v62
	s_mov_b32 s3, 0x2c000
	s_nop 0
	v_addc_co_u32_e32 v43, vcc, 0, v63, vcc
	v_add_co_u32_e32 v46, vcc, s3, v62
	s_mov_b32 s3, 0x30000
	s_nop 0
	v_addc_co_u32_e32 v47, vcc, 0, v63, vcc
	global_load_dwordx4 v[42:45], v[42:43], off nt
	s_nop 0
	global_load_dwordx4 v[46:49], v[46:47], off nt
	v_add_co_u32_e32 v50, vcc, s3, v62
	s_mov_b32 s3, 0x34000
	s_nop 0
	v_addc_co_u32_e32 v51, vcc, 0, v63, vcc
	global_load_dwordx4 v[50:53], v[50:51], off nt
	v_add_co_u32_e32 v54, vcc, s3, v62
	s_mov_b32 s3, 0x38000
	s_nop 0
	v_addc_co_u32_e32 v55, vcc, 0, v63, vcc
	global_load_dwordx4 v[54:57], v[54:55], off nt
	v_add_co_u32_e32 v58, vcc, s3, v62
	s_mov_b32 s3, 0x3c000
	s_nop 0
	v_addc_co_u32_e32 v59, vcc, 0, v63, vcc
	global_load_dwordx4 v[58:61], v[58:59], off nt
	v_add_co_u32_e32 v62, vcc, s3, v62
	s_lshl_b32 s3, s11, 1
	s_nop 0
	v_addc_co_u32_e32 v63, vcc, 0, v63, vcc
	global_load_dwordx4 v[62:65], v[62:63], off nt
	s_cselect_b32 s84, 1, 0
	s_cmp_eq_u32 s32, 1
	s_cbranch_scc1 .Lmy_yield_1
.Lmy_resume_1:
	s_cmp_lg_u32 s84, 0
	s_waitcnt vmcnt(15)
	ds_write2_b32 v69, v2, v3 offset1:1
	ds_write2_b32 v69, v4, v5 offset0:2 offset1:3
	v_add_u32_e32 v2, 0x410, v69
	s_waitcnt vmcnt(14)
	ds_write2_b32 v2, v6, v7 offset1:1
	v_add_u32_e32 v2, 0x418, v69
	ds_write2_b32 v2, v8, v9 offset1:1
	v_add_u32_e32 v2, 0x820, v69
	s_add_u32 s4, s9, s3
	s_addc_u32 s5, s10, 0
	v_lshlrev_b32_e32 v98, 1, v72
	s_waitcnt vmcnt(13)
	ds_write2_b32 v2, v10, v11 offset1:1
	v_add_u32_e32 v2, 0x828, v69
	ds_write2_b32 v2, v12, v13 offset1:1
	v_add_u32_e32 v2, 0xc30, v69
	s_waitcnt vmcnt(12)
	ds_write2_b32 v2, v14, v15 offset1:1
	v_add_u32_e32 v2, 0xc38, v69
	ds_write2_b32 v2, v16, v17 offset1:1
	v_add_u32_e32 v2, 0x1040, v69
	v_lshl_add_u64 v[8:9], s[4:5], 0, v[98:99]
	s_and_b32 s3, s15, 0x60
	s_and_b32 s4, s13, 0x300
	s_waitcnt vmcnt(11)
	ds_write2_b32 v2, v18, v19 offset1:1
	v_add_u32_e32 v2, 0x1048, v69
	ds_write2_b32 v2, v20, v21 offset1:1
	v_add_u32_e32 v2, 0x1450, v69
	s_waitcnt vmcnt(10)
	ds_write2_b32 v2, v22, v23 offset1:1
	v_add_u32_e32 v2, 0x1458, v69
	ds_write2_b32 v2, v24, v25 offset1:1
	v_add_u32_e32 v2, 0x1860, v69
	s_or_b32 s4, s4, s3
	v_add_u32_e32 v14, 0x400, v73
	v_or_b32_e32 v10, s4, v71
	s_waitcnt vmcnt(9)
	ds_write2_b32 v2, v26, v27 offset1:1
	v_add_u32_e32 v2, 0x1868, v69
	ds_write2_b32 v2, v28, v29 offset1:1
	v_add_u32_e32 v2, 0x1c70, v69
	s_waitcnt vmcnt(8)
	ds_write2_b32 v2, v30, v31 offset1:1
	v_add_u32_e32 v2, 0x1c78, v69
	ds_write2_b32 v2, v32, v33 offset1:1
	v_add_u32_e32 v2, 0x2080, v69
	v_lshlrev_b32_e32 v98, 13, v10
	v_lshl_add_u64 v[10:11], v[8:9], 0, v[98:99]
	v_or_b32_e32 v12, s4, v84
	s_waitcnt vmcnt(7)
	ds_write2_b32 v2, v34, v35 offset1:1
	v_add_u32_e32 v2, 0x2088, v69
	ds_write2_b32 v2, v36, v37 offset1:1
	v_add_u32_e32 v2, 0x2490, v69
	s_waitcnt vmcnt(6)
	ds_write2_b32 v2, v38, v39 offset1:1
	v_add_u32_e32 v2, 0x2498, v69
	ds_write2_b32 v2, v40, v41 offset1:1
	v_add_u32_e32 v2, 0x28a0, v69
	v_lshlrev_b32_e32 v98, 13, v12
	v_lshl_add_u64 v[12:13], v[8:9], 0, v[98:99]
	s_waitcnt vmcnt(5)
	ds_write2_b32 v2, v42, v43 offset1:1
	v_add_u32_e32 v2, 0x28a8, v69
	ds_write2_b32 v2, v44, v45 offset1:1
	v_add_u32_e32 v2, 0x2cb0, v69
	s_waitcnt vmcnt(4)
; #define LAS __attribute__((address_space(3)))
; #define LDS_WAIT() asm volatile("s_waitcnt lgkmcnt(0)" ::: "memory")
; __device__ __forceinline__ unsigned pk2(float lo, float hi) { return pg8::cvt_pk_bf16(lo, hi); }
; __device__ __forceinline__ void xpose_item(const float* W, int K, int N, bf16* WT, const float* gain, int cmap, LAS float* scr, int item, int lane) {
;     ...
;     for (int i = 0; i < 16; ++i) { LAS float* d = scr + (4 * i + ks) * XP_STRIDE + n4; d[0] = w[i][0]; d[1] = w[i][1]; d[2] = w[i][2]; d[3] = w[i][3]; }
;     LDS_WAIT(); asm volatile("" ::: "memory");
;     int r0 = n0;
;     if (cmap == 1) { if (n0 < 1024) r0 = 2048 + n0; else if (n0 < 2048) { const int c = n0 - 1024; r0 = (c >> 7) * 256 + (c & 127); } else { const int c = n0 - 2048; r0 = (c >> 7) * 256 + 128 + (c & 127); } }
;     const int c = lane & 7;
; #pragma unroll
;     for (int j = 0; j < 8; ++j) { const int n = (lane >> 3) + 8 * j; const LAS float* sp = scr + (8 * c) * XP_STRIDE + n;
;         v4u o; o.x = pk2(sp[0 * XP_STRIDE], sp[1 * XP_STRIDE]); o.y = pk2(sp[2 * XP_STRIDE], sp[3 * XP_STRIDE]); o.z = pk2(sp[4 * XP_STRIDE], sp[5 * XP_STRIDE]); o.w = pk2(sp[6 * XP_STRIDE], sp[7 * XP_STRIDE]);
;         int rr = r0 + n;
;         if (cmap == 4) { const int cc = rr & 255; rr = (rr & ~255) + 128 * ((cc >> 5) & 1) + 32 * (cc >> 6) + (cc & 31); }
;         *(v4u*)(WT + (size_t)rr * K + k0 + 8 * c) = o; }
	ds_write2_b32 v2, v46, v47 offset1:1
	v_add_u32_e32 v2, 0x2cb8, v69
	ds_write2_b32 v2, v48, v49 offset1:1
	v_add_u32_e32 v2, 0x30c0, v69
	s_waitcnt vmcnt(3)
	ds_write2_b32 v2, v50, v51 offset1:1
	v_add_u32_e32 v2, 0x30c8, v69
	ds_write2_b32 v2, v52, v53 offset1:1
	v_add_u32_e32 v2, 0x34d0, v69
	s_waitcnt vmcnt(2)
	ds_write2_b32 v2, v54, v55 offset1:1
	v_add_u32_e32 v2, 0x34d8, v69
	ds_write2_b32 v2, v56, v57 offset1:1
	v_add_u32_e32 v2, 0x38e0, v69
	s_waitcnt vmcnt(1)
	ds_write2_b32 v2, v58, v59 offset1:1
	v_add_u32_e32 v2, 0x38e8, v69
	ds_write2_b32 v2, v60, v61 offset1:1
	v_add_u32_e32 v2, 0x3cf0, v69
	s_waitcnt vmcnt(0)
	ds_write2_b32 v2, v62, v63 offset1:1
	v_add_u32_e32 v2, 0x3cf8, v69
	ds_write2_b32 v2, v64, v65 offset1:1
	s_waitcnt lgkmcnt(0)
	ds_read2_b32 v[2:3], v73 offset1:65
	s_waitcnt lgkmcnt(0)
	v_cvt_pk_bf16_f32 v2, v2, v3
	ds_read2_b32 v[4:5], v73 offset0:130 offset1:195
	s_waitcnt lgkmcnt(0)
	v_cvt_pk_bf16_f32 v3, v4, v5
	ds_read2_b32 v[4:5], v14 offset0:4 offset1:69
	s_waitcnt lgkmcnt(0)
	v_cvt_pk_bf16_f32 v4, v4, v5
	ds_read2_b32 v[6:7], v14 offset0:134 offset1:199
	s_waitcnt lgkmcnt(0)
	v_cvt_pk_bf16_f32 v5, v6, v7
	ds_read2_b32 v[6:7], v73 offset0:8 offset1:73
	global_store_dwordx4 v[10:11], v[2:5], off sc1
	s_waitcnt lgkmcnt(0)
	s_nop 0
	v_cvt_pk_bf16_f32 v2, v6, v7
	ds_read2_b32 v[4:5], v73 offset0:138 offset1:203
	s_waitcnt lgkmcnt(0)
	v_cvt_pk_bf16_f32 v3, v4, v5
	ds_read2_b32 v[4:5], v14 offset0:12 offset1:77
	s_waitcnt lgkmcnt(0)
	v_cvt_pk_bf16_f32 v4, v4, v5
	ds_read2_b32 v[6:7], v14 offset0:142 offset1:207
	s_waitcnt lgkmcnt(0)
	v_cvt_pk_bf16_f32 v5, v6, v7
	ds_read2_b32 v[6:7], v73 offset0:16 offset1:81
	global_store_dwordx4 v[12:13], v[2:5], off sc1
	v_or_b32_e32 v12, s4, v85
	v_lshlrev_b32_e32 v98, 13, v12
	s_waitcnt lgkmcnt(0)
	v_cvt_pk_bf16_f32 v2, v6, v7
	ds_read2_b32 v[4:5], v73 offset0:146 offset1:211
	s_waitcnt lgkmcnt(0)
	v_cvt_pk_bf16_f32 v3, v4, v5
	ds_read2_b32 v[4:5], v14 offset0:20 offset1:85
	s_waitcnt lgkmcnt(0)
	v_cvt_pk_bf16_f32 v4, v4, v5
	ds_read2_b32 v[6:7], v14 offset0:150 offset1:215
	s_waitcnt lgkmcnt(0)
	v_cvt_pk_bf16_f32 v5, v6, v7
	v_lshl_add_u64 v[12:13], v[8:9], 0, v[98:99]
	ds_read2_b32 v[6:7], v73 offset0:24 offset1:89
	global_store_dwordx4 v[12:13], v[2:5], off sc1
	v_or_b32_e32 v12, s4, v86
	v_lshlrev_b32_e32 v98, 13, v12
	s_waitcnt lgkmcnt(0)
	v_cvt_pk_bf16_f32 v2, v6, v7
	ds_read2_b32 v[4:5], v73 offset0:154 offset1:219
	s_waitcnt lgkmcnt(0)
	v_cvt_pk_bf16_f32 v3, v4, v5
	ds_read2_b32 v[4:5], v14 offset0:28 offset1:93
	s_waitcnt lgkmcnt(0)
	v_cvt_pk_bf16_f32 v4, v4, v5
	ds_read2_b32 v[6:7], v14 offset0:158 offset1:223
	s_waitcnt lgkmcnt(0)
	v_cvt_pk_bf16_f32 v5, v6, v7
	v_lshl_add_u64 v[12:13], v[8:9], 0, v[98:99]
	ds_read2_b32 v[6:7], v73 offset0:32 offset1:97
	global_store_dwordx4 v[12:13], v[2:5], off sc1
	s_mov_b32 s4, 0x100000
	v_add_co_u32_e32 v10, vcc, s4, v10
	s_waitcnt lgkmcnt(0)
	v_cvt_pk_bf16_f32 v2, v6, v7
	ds_read2_b32 v[4:5], v73 offset0:162 offset1:227
	s_waitcnt lgkmcnt(0)
	v_cvt_pk_bf16_f32 v3, v4, v5
	ds_read2_b32 v[4:5], v14 offset0:36 offset1:101
	s_waitcnt lgkmcnt(0)
	v_cvt_pk_bf16_f32 v4, v4, v5
	ds_read2_b32 v[6:7], v14 offset0:166 offset1:231
	s_waitcnt lgkmcnt(0)
	v_cvt_pk_bf16_f32 v5, v6, v7
	v_addc_co_u32_e32 v11, vcc, 0, v11, vcc
	ds_read2_b32 v[6:7], v73 offset0:40 offset1:105
	global_store_dwordx4 v[10:11], v[2:5], off sc1
	v_add_u32_e32 v12, s13, v71
	s_waitcnt lgkmcnt(0)
	v_cvt_pk_bf16_f32 v2, v6, v7
	ds_read2_b32 v[4:5], v73 offset0:170 offset1:235
	s_waitcnt lgkmcnt(0)
	v_cvt_pk_bf16_f32 v3, v4, v5
	ds_read2_b32 v[4:5], v14 offset0:44 offset1:109
	s_waitcnt lgkmcnt(0)
	v_cvt_pk_bf16_f32 v4, v4, v5
	ds_read2_b32 v[6:7], v14 offset0:174 offset1:239
	s_waitcnt lgkmcnt(0)
	v_cvt_pk_bf16_f32 v5, v6, v7
	v_add_u32_e32 v6, 40, v12
	v_and_b32_e32 v6, 0x30f, v6
	v_or_b32_e32 v6, s3, v6
	v_lshlrev_b32_e32 v98, 13, v6
	v_lshl_add_u64 v[6:7], v[8:9], 0, v[98:99]
	v_add_co_u32_e32 v6, vcc, s4, v6
	ds_read2_b32 v[10:11], v73 offset0:48 offset1:113
	s_nop 0
	v_addc_co_u32_e32 v7, vcc, 0, v7, vcc
	global_store_dwordx4 v[6:7], v[2:5], off sc1
	s_waitcnt lgkmcnt(0)
	s_nop 0
	v_cvt_pk_bf16_f32 v2, v10, v11
	ds_read2_b32 v[4:5], v73 offset0:178 offset1:243
	s_waitcnt lgkmcnt(0)
	v_cvt_pk_bf16_f32 v3, v4, v5
	ds_read2_b32 v[4:5], v14 offset0:52 offset1:117
	s_waitcnt lgkmcnt(0)
	v_cvt_pk_bf16_f32 v4, v4, v5
	ds_read2_b32 v[6:7], v14 offset0:182 offset1:247
	s_waitcnt lgkmcnt(0)
	v_cvt_pk_bf16_f32 v5, v6, v7
	v_add_u32_e32 v6, 48, v12
	v_and_b32_e32 v6, 0x317, v6
	v_or_b32_e32 v6, s3, v6
	v_lshlrev_b32_e32 v98, 13, v6
	v_lshl_add_u64 v[6:7], v[8:9], 0, v[98:99]
	v_add_co_u32_e32 v6, vcc, s4, v6
	ds_read2_b32 v[10:11], v73 offset0:56 offset1:121
	s_nop 0
	v_addc_co_u32_e32 v7, vcc, 0, v7, vcc
	global_store_dwordx4 v[6:7], v[2:5], off sc1
	s_mov_b64 s[4:5], 0
	s_waitcnt lgkmcnt(0)
	v_cvt_pk_bf16_f32 v2, v10, v11
	ds_read2_b32 v[4:5], v73 offset0:186 offset1:251
	s_waitcnt lgkmcnt(0)
	v_cvt_pk_bf16_f32 v3, v4, v5
	ds_read2_b32 v[4:5], v14 offset0:60 offset1:125
	s_waitcnt lgkmcnt(0)
	v_cvt_pk_bf16_f32 v4, v4, v5
	ds_read2_b32 v[6:7], v14 offset0:190 offset1:255
	s_waitcnt lgkmcnt(0)
	v_cvt_pk_bf16_f32 v5, v6, v7
	v_add_u32_e32 v6, 56, v12
	v_and_b32_e32 v6, 0x31f, v6
	v_or_b32_e32 v6, s3, v6
	v_lshlrev_b32_e32 v98, 13, v6
	v_lshl_add_u64 v[6:7], v[8:9], 0, v[98:99]
	v_add_co_u32_e32 v6, vcc, 0x100000, v6
	s_nop 1
	v_addc_co_u32_e32 v7, vcc, 0, v7, vcc
	global_store_dwordx4 v[6:7], v[2:5], off sc1
	s_waitcnt lgkmcnt(0)
; __device__ __forceinline__ void xpose_item(const float* W, int K, int N, bf16* WT, const float* gain, int cmap, LAS float* scr, int item, int lane) {
;     ...
;     f32x4 w[16];
; #pragma unroll
;     for (int i = 0; i < 16; ++i) w[i] = __builtin_nontemporal_load((const f32x4*)(W + (size_t)(k0 + 4 * i + ks) * N + n0 + n4));
;     if (gain) {
; #pragma unroll
;         for (int i = 0; i < 16; ++i) w[i] = w[i] * gain[k0 + 4 * i + ks];
;     }
; __device__ __forceinline__ void prologue(const Args& a, LAS unsigned char* lds, int vcu, int G, int wave, int lane, int tid) {
;     ...
;         if (r < 4 * I_UP) { const int l = r / I_UP; r -= l * I_UP; xpose_item(a.in[11] + (size_t)l * 1024 * 4096, 1024, 4096, (bf16*)(ws + WS_WUP) + (size_t)l * 4096 * 1024, nmlp + l * 1024, 4, scr, r, lane); continue; } r -= 4 * I_UP;
.LBB0_536:
	s_andn2_b64 vcc, exec, s[4:5]
	s_cbranch_vccnz .LBB0_540
	s_add_i32 s4, s7, 0x1000
	s_lshr_b32 s86, s4, 10
	s_lshl_b64 s[8:9], s[86:87], 24
	s_add_u32 s5, s54, s8
	s_addc_u32 s9, s55, s9
	s_and_b32 s8, s13, 0xfc0
	s_and_b32 s3, s4, 0x3c0
	s_lshl_b32 s8, s8, 2
	s_add_u32 s8, s5, s8
	v_or_b32_e32 v82, s3, v67
	s_addc_u32 s9, s9, 0
	v_lshlrev_b32_e32 v98, 2, v70
	v_lshl_add_u64 v[54:55], s[8:9], 0, v[98:99]
	v_lshlrev_b32_e32 v98, 14, v82
	v_lshl_add_u64 v[2:3], v[54:55], 0, v[98:99]
	v_or_b32_e32 v4, 0x10000, v98
	v_mov_b32_e32 v5, v99
	v_or_b32_e32 v6, 0x20000, v98
	v_mov_b32_e32 v7, v99
	v_or_b32_e32 v8, 0x30000, v98
	v_mov_b32_e32 v9, v99
	v_or_b32_e32 v14, 0x40000, v98
	v_mov_b32_e32 v15, v99
	v_or_b32_e32 v16, 0x50000, v98
	v_mov_b32_e32 v17, v99
	v_or_b32_e32 v22, 0x60000, v98
	v_mov_b32_e32 v23, v99
	v_or_b32_e32 v24, 0x70000, v98
	v_mov_b32_e32 v25, v99
	v_or_b32_e32 v30, 0x80000, v98
	v_mov_b32_e32 v31, v99
	v_or_b32_e32 v32, 0x90000, v98
	v_mov_b32_e32 v33, v99
	v_or_b32_e32 v38, 0xa0000, v98
	v_mov_b32_e32 v39, v99
	v_or_b32_e32 v40, 0xb0000, v98
	v_mov_b32_e32 v41, v99
	v_or_b32_e32 v46, 0xc0000, v98
	v_mov_b32_e32 v47, v99
	v_or_b32_e32 v48, 0xd0000, v98
	v_mov_b32_e32 v49, v99
	v_or_b32_e32 v56, 0xe0000, v98
	v_mov_b32_e32 v57, v99
	v_or_b32_e32 v98, 0xf0000, v98
	v_lshl_add_u64 v[4:5], v[54:55], 0, v[4:5]
	v_lshl_add_u64 v[6:7], v[54:55], 0, v[6:7]
	v_lshl_add_u64 v[8:9], v[54:55], 0, v[8:9]
	v_lshl_add_u64 v[14:15], v[54:55], 0, v[14:15]
	v_lshl_add_u64 v[16:17], v[54:55], 0, v[16:17]
	v_lshl_add_u64 v[22:23], v[54:55], 0, v[22:23]
	v_lshl_add_u64 v[24:25], v[54:55], 0, v[24:25]
	v_lshl_add_u64 v[30:31], v[54:55], 0, v[30:31]
	v_lshl_add_u64 v[32:33], v[54:55], 0, v[32:33]
	v_lshl_add_u64 v[38:39], v[54:55], 0, v[38:39]
	v_lshl_add_u64 v[40:41], v[54:55], 0, v[40:41]
	v_lshl_add_u64 v[46:47], v[54:55], 0, v[46:47]
	v_lshl_add_u64 v[48:49], v[54:55], 0, v[48:49]
	v_lshl_add_u64 v[56:57], v[54:55], 0, v[56:57]
	v_lshl_add_u64 v[54:55], v[54:55], 0, v[98:99]
	global_load_dwordx4 v[10:13], v[2:3], off nt
	s_nop 0
	global_load_dwordx4 v[2:5], v[4:5], off nt
	s_nop 0
	global_load_dwordx4 v[18:21], v[6:7], off nt
	s_nop 0
	global_load_dwordx4 v[6:9], v[8:9], off nt
	s_nop 0
	global_load_dwordx4 v[26:29], v[14:15], off nt
	s_nop 0
	global_load_dwordx4 v[14:17], v[16:17], off nt
	s_nop 0
	global_load_dwordx4 v[34:37], v[22:23], off nt
	s_nop 0
	global_load_dwordx4 v[22:25], v[24:25], off nt
	s_nop 0
	global_load_dwordx4 v[42:45], v[30:31], off nt
	s_nop 0
	global_load_dwordx4 v[30:33], v[32:33], off nt
	s_nop 0
	global_load_dwordx4 v[50:53], v[38:39], off nt
	s_nop 0
	global_load_dwordx4 v[38:41], v[40:41], off nt
	s_nop 0
	global_load_dwordx4 v[58:61], v[46:47], off nt
	s_nop 0
	global_load_dwordx4 v[46:49], v[48:49], off nt
	s_nop 0
	global_load_dwordx4 v[62:65], v[56:57], off nt
	s_nop 0
	global_load_dwordx4 v[54:57], v[54:55], off nt
	v_readlane_b32 s8, v253, 7
	v_readlane_b32 s9, v253, 8
	s_andn2_b64 vcc, exec, s[8:9]
	s_cbranch_vccnz .LBB0_539
	s_and_b32 s4, s4, 0xfffffc00
	s_mov_b32 s5, s87
	v_readlane_b32 s68, v253, 18
	s_lshl_b64 s[4:5], s[4:5], 2
	v_readlane_b32 s74, v253, 24
	v_readlane_b32 s75, v253, 25
	s_add_u32 s4, s74, s4
	s_addc_u32 s5, s75, s5
	v_lshlrev_b32_e32 v83, 2, v82
	global_load_dword v82, v83, s[4:5]
	global_load_dword v94, v83, s[4:5] offset:16
	global_load_dword v96, v83, s[4:5] offset:32
	global_load_dword v98, v83, s[4:5] offset:48
	global_load_dword v100, v83, s[4:5] offset:64
	global_load_dword v102, v83, s[4:5] offset:80
	global_load_dword v104, v83, s[4:5] offset:96
	global_load_dword v106, v83, s[4:5] offset:112
	global_load_dword v108, v83, s[4:5] offset:128
	global_load_dword v110, v83, s[4:5] offset:144
	global_load_dword v112, v83, s[4:5] offset:160
	global_load_dword v114, v83, s[4:5] offset:176
	global_load_dword v116, v83, s[4:5] offset:192
	global_load_dword v118, v83, s[4:5] offset:208
	global_load_dword v120, v83, s[4:5] offset:224
	global_load_dword v122, v83, s[4:5] offset:240
	v_readlane_b32 s69, v253, 19
	v_readlane_b32 s70, v253, 20
	v_readlane_b32 s71, v253, 21
	v_readlane_b32 s72, v253, 22
	v_readlane_b32 s73, v253, 23
	v_readlane_b32 s76, v253, 26
	v_readlane_b32 s77, v253, 27
	v_readlane_b32 s78, v253, 28
	v_readlane_b32 s79, v253, 29
	v_readlane_b32 s80, v253, 30
	v_readlane_b32 s81, v253, 31
	v_readlane_b32 s82, v253, 32
	v_readlane_b32 s83, v253, 33
	s_cselect_b32 s84, 1, 0
	s_cmp_eq_u32 s32, 1
	s_cbranch_scc1 .Lmy_yield_2
.Lmy_resume_2:
	s_cmp_lg_u32 s84, 0
	s_waitcnt vmcnt(15)
	v_pk_mul_f32 v[12:13], v[12:13], v[82:83] op_sel_hi:[1,0]
	v_pk_mul_f32 v[10:11], v[10:11], v[82:83] op_sel_hi:[1,0]
	s_waitcnt vmcnt(14)
	v_pk_mul_f32 v[4:5], v[4:5], v[94:95] op_sel_hi:[1,0]
	v_pk_mul_f32 v[2:3], v[2:3], v[94:95] op_sel_hi:[1,0]
	s_waitcnt vmcnt(13)
	v_pk_mul_f32 v[20:21], v[20:21], v[96:97] op_sel_hi:[1,0]
	v_pk_mul_f32 v[18:19], v[18:19], v[96:97] op_sel_hi:[1,0]
	s_waitcnt vmcnt(12)
	v_pk_mul_f32 v[8:9], v[8:9], v[98:99] op_sel_hi:[1,0]
	v_pk_mul_f32 v[6:7], v[6:7], v[98:99] op_sel_hi:[1,0]
	s_waitcnt vmcnt(11)
	v_pk_mul_f32 v[28:29], v[28:29], v[100:101] op_sel_hi:[1,0]
	v_pk_mul_f32 v[26:27], v[26:27], v[100:101] op_sel_hi:[1,0]
	s_waitcnt vmcnt(10)
	v_pk_mul_f32 v[16:17], v[16:17], v[102:103] op_sel_hi:[1,0]
	v_pk_mul_f32 v[14:15], v[14:15], v[102:103] op_sel_hi:[1,0]
	s_waitcnt vmcnt(9)
	v_pk_mul_f32 v[36:37], v[36:37], v[104:105] op_sel_hi:[1,0]
	v_pk_mul_f32 v[34:35], v[34:35], v[104:105] op_sel_hi:[1,0]
	s_waitcnt vmcnt(8)
	v_pk_mul_f32 v[24:25], v[24:25], v[106:107] op_sel_hi:[1,0]
	v_pk_mul_f32 v[22:23], v[22:23], v[106:107] op_sel_hi:[1,0]
	s_waitcnt vmcnt(7)
	v_pk_mul_f32 v[44:45], v[44:45], v[108:109] op_sel_hi:[1,0]
	v_pk_mul_f32 v[42:43], v[42:43], v[108:109] op_sel_hi:[1,0]
	s_waitcnt vmcnt(6)
	v_pk_mul_f32 v[32:33], v[32:33], v[110:111] op_sel_hi:[1,0]
	v_pk_mul_f32 v[30:31], v[30:31], v[110:111] op_sel_hi:[1,0]
	s_waitcnt vmcnt(5)
	v_pk_mul_f32 v[52:53], v[52:53], v[112:113] op_sel_hi:[1,0]
	v_pk_mul_f32 v[50:51], v[50:51], v[112:113] op_sel_hi:[1,0]
	s_waitcnt vmcnt(4)
	v_pk_mul_f32 v[40:41], v[40:41], v[114:115] op_sel_hi:[1,0]
	v_pk_mul_f32 v[38:39], v[38:39], v[114:115] op_sel_hi:[1,0]
	s_waitcnt vmcnt(3)
	v_pk_mul_f32 v[60:61], v[60:61], v[116:117] op_sel_hi:[1,0]
	v_pk_mul_f32 v[58:59], v[58:59], v[116:117] op_sel_hi:[1,0]
	s_waitcnt vmcnt(2)
	v_pk_mul_f32 v[48:49], v[48:49], v[118:119] op_sel_hi:[1,0]
	v_pk_mul_f32 v[46:47], v[46:47], v[118:119] op_sel_hi:[1,0]
	s_waitcnt vmcnt(1)
	v_pk_mul_f32 v[64:65], v[64:65], v[120:121] op_sel_hi:[1,0]
	v_pk_mul_f32 v[62:63], v[62:63], v[120:121] op_sel_hi:[1,0]
	s_waitcnt vmcnt(0)
	v_pk_mul_f32 v[56:57], v[56:57], v[122:123] op_sel_hi:[1,0]
	v_pk_mul_f32 v[54:55], v[54:55], v[122:123] op_sel_hi:[1,0]

; #define LAS __attribute__((address_space(3)))
; #define LDS_WAIT() asm volatile("s_waitcnt lgkmcnt(0)" ::: "memory")
; __device__ __forceinline__ unsigned pk2(float lo, float hi) { return pg8::cvt_pk_bf16(lo, hi); }
; __device__ __forceinline__ void xpose_item(const float* W, int K, int N, bf16* WT, const float* gain, int cmap, LAS float* scr, int item, int lane) {
;     ...
;     for (int i = 0; i < 16; ++i) { LAS float* d = scr + (4 * i + ks) * XP_STRIDE + n4; d[0] = w[i][0]; d[1] = w[i][1]; d[2] = w[i][2]; d[3] = w[i][3]; }
;     LDS_WAIT(); asm volatile("" ::: "memory");
;     int r0 = n0;
;     if (cmap == 1) { if (n0 < 1024) r0 = 2048 + n0; else if (n0 < 2048) { const int c = n0 - 1024; r0 = (c >> 7) * 256 + (c & 127); } else { const int c = n0 - 2048; r0 = (c >> 7) * 256 + 128 + (c & 127); } }
;     const int c = lane & 7;
; #pragma unroll
;     for (int j = 0; j < 8; ++j) { const int n = (lane >> 3) + 8 * j; const LAS float* sp = scr + (8 * c) * XP_STRIDE + n;
;         v4u o; o.x = pk2(sp[0 * XP_STRIDE], sp[1 * XP_STRIDE]); o.y = pk2(sp[2 * XP_STRIDE], sp[3 * XP_STRIDE]); o.z = pk2(sp[4 * XP_STRIDE], sp[5 * XP_STRIDE]); o.w = pk2(sp[6 * XP_STRIDE], sp[7 * XP_STRIDE]);
;         int rr = r0 + n;
;         if (cmap == 4) { const int cc = rr & 255; rr = (rr & ~255) + 128 * ((cc >> 5) & 1) + 32 * (cc >> 6) + (cc & 31); }
;         *(v4u*)(WT + (size_t)rr * K + k0 + 8 * c) = o; }
.Lmy_resume_3:
	s_cmp_lg_u32 s84, 0
	s_waitcnt vmcnt(15)
	ds_write2_b32 v69, v10, v11 offset1:1
	ds_write2_b32 v69, v12, v13 offset0:2 offset1:3
	v_add_u32_e32 v10, 0x410, v69
	s_waitcnt vmcnt(14)
	ds_write2_b32 v10, v2, v3 offset1:1
	v_add_u32_e32 v2, 0x418, v69
	ds_write2_b32 v2, v4, v5 offset1:1
	v_add_u32_e32 v2, 0x820, v69
	s_waitcnt vmcnt(13)
	ds_write2_b32 v2, v18, v19 offset1:1
	v_add_u32_e32 v2, 0x828, v69
	ds_write2_b32 v2, v20, v21 offset1:1
	v_add_u32_e32 v2, 0xc30, v69
	s_waitcnt vmcnt(12)
	ds_write2_b32 v2, v6, v7 offset1:1
	v_add_u32_e32 v2, 0xc38, v69
	ds_write2_b32 v2, v8, v9 offset1:1
	v_add_u32_e32 v2, 0x1040, v69
	s_waitcnt vmcnt(11)
	ds_write2_b32 v2, v26, v27 offset1:1
	v_add_u32_e32 v2, 0x1048, v69
	ds_write2_b32 v2, v28, v29 offset1:1
	v_add_u32_e32 v2, 0x1450, v69
	s_waitcnt vmcnt(10)
	ds_write2_b32 v2, v14, v15 offset1:1
	v_add_u32_e32 v2, 0x1458, v69
	ds_write2_b32 v2, v16, v17 offset1:1
	v_add_u32_e32 v2, 0x1860, v69
	s_waitcnt vmcnt(9)
	ds_write2_b32 v2, v34, v35 offset1:1
	v_add_u32_e32 v2, 0x1868, v69
	ds_write2_b32 v2, v36, v37 offset1:1
	v_add_u32_e32 v2, 0x1c70, v69
	s_waitcnt vmcnt(8)
	ds_write2_b32 v2, v22, v23 offset1:1
	v_add_u32_e32 v2, 0x1c78, v69
	ds_write2_b32 v2, v24, v25 offset1:1
	v_add_u32_e32 v2, 0x2080, v69
	s_waitcnt vmcnt(7)
	ds_write2_b32 v2, v42, v43 offset1:1
	v_add_u32_e32 v2, 0x2088, v69
	ds_write2_b32 v2, v44, v45 offset1:1
	v_add_u32_e32 v2, 0x2490, v69
	s_waitcnt vmcnt(6)
	ds_write2_b32 v2, v30, v31 offset1:1
	v_add_u32_e32 v2, 0x2498, v69
	ds_write2_b32 v2, v32, v33 offset1:1
	v_add_u32_e32 v2, 0x28a0, v69
	s_waitcnt vmcnt(5)
	ds_write2_b32 v2, v50, v51 offset1:1
	v_add_u32_e32 v2, 0x28a8, v69
	ds_write2_b32 v2, v52, v53 offset1:1
	v_add_u32_e32 v2, 0x2cb0, v69
	s_waitcnt vmcnt(4)
	ds_write2_b32 v2, v38, v39 offset1:1
	v_add_u32_e32 v2, 0x2cb8, v69
	ds_write2_b32 v2, v40, v41 offset1:1
	v_add_u32_e32 v2, 0x30c0, v69
	s_waitcnt vmcnt(3)
	ds_write2_b32 v2, v58, v59 offset1:1
	v_add_u32_e32 v2, 0x30c8, v69
	ds_write2_b32 v2, v60, v61 offset1:1
	v_add_u32_e32 v2, 0x34d0, v69
	s_waitcnt vmcnt(2)
	ds_write2_b32 v2, v46, v47 offset1:1
	v_add_u32_e32 v2, 0x34d8, v69
	ds_write2_b32 v2, v48, v49 offset1:1
	v_add_u32_e32 v2, 0x38e0, v69
	s_waitcnt vmcnt(1)
	ds_write2_b32 v2, v62, v63 offset1:1
	v_add_u32_e32 v2, 0x38e8, v69
	s_lshl_b64 s[4:5], s[86:87], 23
	v_readlane_b32 s8, v253, 5
	ds_write2_b32 v2, v64, v65 offset1:1
	v_add_u32_e32 v2, 0x3cf0, v69
	s_add_u32 s4, s8, s4
	v_readlane_b32 s8, v253, 6
	s_waitcnt vmcnt(0)
	ds_write2_b32 v2, v54, v55 offset1:1
	v_add_u32_e32 v2, 0x3cf8, v69
	s_addc_u32 s5, s8, s5
	s_lshl_b32 s3, s3, 1
	ds_write2_b32 v2, v56, v57 offset1:1
	s_add_u32 s4, s4, s3
	s_waitcnt lgkmcnt(0)
	s_addc_u32 s5, s5, 0
	v_lshlrev_b32_e32 v98, 1, v72
	v_lshl_add_u64 v[8:9], s[4:5], 0, v[98:99]
	s_and_b32 s3, s15, 0x60
	s_and_b32 s4, s13, 0xf00
	ds_read2_b32 v[2:3], v73 offset1:65
	s_or_b32 s4, s4, s3
	s_waitcnt lgkmcnt(0)
	v_cvt_pk_bf16_f32 v2, v2, v3
	ds_read2_b32 v[4:5], v73 offset0:130 offset1:195
	v_add_u32_e32 v14, 0x400, v73
	v_or_b32_e32 v10, s4, v71
	s_waitcnt lgkmcnt(0)
	v_cvt_pk_bf16_f32 v3, v4, v5
	ds_read2_b32 v[4:5], v14 offset0:4 offset1:69
	v_lshlrev_b32_e32 v98, 11, v10
	s_waitcnt lgkmcnt(0)
	v_cvt_pk_bf16_f32 v4, v4, v5
	ds_read2_b32 v[6:7], v14 offset0:134 offset1:199
	s_waitcnt lgkmcnt(0)
	v_cvt_pk_bf16_f32 v5, v6, v7
	v_lshl_add_u64 v[10:11], v[8:9], 0, v[98:99]
	ds_read2_b32 v[6:7], v73 offset0:8 offset1:73
	global_store_dwordx4 v[10:11], v[2:5], off sc1
	v_or_b32_e32 v12, s4, v84
	v_lshlrev_b32_e32 v98, 11, v12
	s_waitcnt lgkmcnt(0)
	v_cvt_pk_bf16_f32 v2, v6, v7
	ds_read2_b32 v[4:5], v73 offset0:138 offset1:203
	s_waitcnt lgkmcnt(0)
	v_cvt_pk_bf16_f32 v3, v4, v5
	ds_read2_b32 v[4:5], v14 offset0:12 offset1:77
	s_waitcnt lgkmcnt(0)
	v_cvt_pk_bf16_f32 v4, v4, v5
	ds_read2_b32 v[6:7], v14 offset0:142 offset1:207
	s_waitcnt lgkmcnt(0)
; #define LAS __attribute__((address_space(3)))
; __device__ __forceinline__ unsigned pk2(float lo, float hi) { return pg8::cvt_pk_bf16(lo, hi); }
; __device__ __forceinline__ void xpose_item(const float* W, int K, int N, bf16* WT, const float* gain, int cmap, LAS float* scr, int item, int lane) {
;     ...
;     const int c = lane & 7;
; #pragma unroll
;     for (int j = 0; j < 8; ++j) { const int n = (lane >> 3) + 8 * j; const LAS float* sp = scr + (8 * c) * XP_STRIDE + n;
;         v4u o; o.x = pk2(sp[0 * XP_STRIDE], sp[1 * XP_STRIDE]); o.y = pk2(sp[2 * XP_STRIDE], sp[3 * XP_STRIDE]); o.z = pk2(sp[4 * XP_STRIDE], sp[5 * XP_STRIDE]); o.w = pk2(sp[6 * XP_STRIDE], sp[7 * XP_STRIDE]);
;         int rr = r0 + n;
;         if (cmap == 4) { const int cc = rr & 255; rr = (rr & ~255) + 128 * ((cc >> 5) & 1) + 32 * (cc >> 6) + (cc & 31); }
;         *(v4u*)(WT + (size_t)rr * K + k0 + 8 * c) = o; }
	v_cvt_pk_bf16_f32 v5, v6, v7
	v_lshl_add_u64 v[12:13], v[8:9], 0, v[98:99]
	ds_read2_b32 v[6:7], v73 offset0:16 offset1:81
	global_store_dwordx4 v[12:13], v[2:5], off sc1
	v_or_b32_e32 v12, s4, v85
	v_lshlrev_b32_e32 v98, 11, v12
	s_waitcnt lgkmcnt(0)
	v_cvt_pk_bf16_f32 v2, v6, v7
	ds_read2_b32 v[4:5], v73 offset0:146 offset1:211
	s_waitcnt lgkmcnt(0)
	v_cvt_pk_bf16_f32 v3, v4, v5
	ds_read2_b32 v[4:5], v14 offset0:20 offset1:85
	s_waitcnt lgkmcnt(0)
	v_cvt_pk_bf16_f32 v4, v4, v5
	ds_read2_b32 v[6:7], v14 offset0:150 offset1:215
	s_waitcnt lgkmcnt(0)
	v_cvt_pk_bf16_f32 v5, v6, v7
	v_lshl_add_u64 v[12:13], v[8:9], 0, v[98:99]
	ds_read2_b32 v[6:7], v73 offset0:24 offset1:89
	global_store_dwordx4 v[12:13], v[2:5], off sc1
	v_or_b32_e32 v12, s4, v86
	v_lshlrev_b32_e32 v98, 11, v12
	s_waitcnt lgkmcnt(0)
	v_cvt_pk_bf16_f32 v2, v6, v7
	ds_read2_b32 v[4:5], v73 offset0:154 offset1:219
	s_waitcnt lgkmcnt(0)
	v_cvt_pk_bf16_f32 v3, v4, v5
	ds_read2_b32 v[4:5], v14 offset0:28 offset1:93
	s_waitcnt lgkmcnt(0)
	v_cvt_pk_bf16_f32 v4, v4, v5
	ds_read2_b32 v[6:7], v14 offset0:158 offset1:223
	s_waitcnt lgkmcnt(0)
	v_cvt_pk_bf16_f32 v5, v6, v7
	v_lshl_add_u64 v[12:13], v[8:9], 0, v[98:99]
	ds_read2_b32 v[6:7], v73 offset0:32 offset1:97
	global_store_dwordx4 v[12:13], v[2:5], off sc1
	s_mov_b32 s4, 0x40000
	v_add_co_u32_e32 v10, vcc, s4, v10
	s_waitcnt lgkmcnt(0)
	v_cvt_pk_bf16_f32 v2, v6, v7
	ds_read2_b32 v[4:5], v73 offset0:162 offset1:227
	s_waitcnt lgkmcnt(0)
	v_cvt_pk_bf16_f32 v3, v4, v5
	ds_read2_b32 v[4:5], v14 offset0:36 offset1:101
	s_waitcnt lgkmcnt(0)
	v_cvt_pk_bf16_f32 v4, v4, v5
	ds_read2_b32 v[6:7], v14 offset0:166 offset1:231
	s_waitcnt lgkmcnt(0)
	v_cvt_pk_bf16_f32 v5, v6, v7
	v_addc_co_u32_e32 v11, vcc, 0, v11, vcc
	ds_read2_b32 v[6:7], v73 offset0:40 offset1:105
	global_store_dwordx4 v[10:11], v[2:5], off sc1
	v_add_u32_e32 v12, s13, v71
	s_waitcnt lgkmcnt(0)
	v_cvt_pk_bf16_f32 v2, v6, v7
	ds_read2_b32 v[4:5], v73 offset0:170 offset1:235
	s_waitcnt lgkmcnt(0)
	v_cvt_pk_bf16_f32 v3, v4, v5
	ds_read2_b32 v[4:5], v14 offset0:44 offset1:109
	s_waitcnt lgkmcnt(0)
	v_cvt_pk_bf16_f32 v4, v4, v5
	ds_read2_b32 v[6:7], v14 offset0:174 offset1:239
	s_waitcnt lgkmcnt(0)
	v_cvt_pk_bf16_f32 v5, v6, v7
	v_add_u32_e32 v6, 40, v12
	v_and_b32_e32 v6, 0xf0f, v6
	v_or_b32_e32 v6, s3, v6
	v_lshlrev_b32_e32 v98, 11, v6
	v_lshl_add_u64 v[6:7], v[8:9], 0, v[98:99]
	v_add_co_u32_e32 v6, vcc, s4, v6
	ds_read2_b32 v[10:11], v73 offset0:48 offset1:113
	s_nop 0
	v_addc_co_u32_e32 v7, vcc, 0, v7, vcc
	global_store_dwordx4 v[6:7], v[2:5], off sc1
	s_waitcnt lgkmcnt(0)
	s_nop 0
	v_cvt_pk_bf16_f32 v2, v10, v11
	ds_read2_b32 v[4:5], v73 offset0:178 offset1:243
	s_waitcnt lgkmcnt(0)
	v_cvt_pk_bf16_f32 v3, v4, v5
	ds_read2_b32 v[4:5], v14 offset0:52 offset1:117
	s_waitcnt lgkmcnt(0)
	v_cvt_pk_bf16_f32 v4, v4, v5
	ds_read2_b32 v[6:7], v14 offset0:182 offset1:247
	s_waitcnt lgkmcnt(0)
	v_cvt_pk_bf16_f32 v5, v6, v7
	v_add_u32_e32 v6, 48, v12
	v_and_b32_e32 v6, 0xf17, v6
	v_or_b32_e32 v6, s3, v6
	v_lshlrev_b32_e32 v98, 11, v6
	v_lshl_add_u64 v[6:7], v[8:9], 0, v[98:99]
	v_add_co_u32_e32 v6, vcc, s4, v6
	ds_read2_b32 v[10:11], v73 offset0:56 offset1:121
	s_nop 0
	v_addc_co_u32_e32 v7, vcc, 0, v7, vcc
	global_store_dwordx4 v[6:7], v[2:5], off sc1
	s_waitcnt lgkmcnt(0)
	s_nop 0
	v_cvt_pk_bf16_f32 v2, v10, v11
	ds_read2_b32 v[4:5], v73 offset0:186 offset1:251
	s_waitcnt lgkmcnt(0)
	v_cvt_pk_bf16_f32 v3, v4, v5
	ds_read2_b32 v[4:5], v14 offset0:60 offset1:125
	s_waitcnt lgkmcnt(0)
	v_cvt_pk_bf16_f32 v4, v4, v5
	ds_read2_b32 v[6:7], v14 offset0:190 offset1:255
	s_waitcnt lgkmcnt(0)
	v_cvt_pk_bf16_f32 v5, v6, v7
	v_add_u32_e32 v6, 56, v12
	v_and_b32_e32 v6, 0xf1f, v6
	v_or_b32_e32 v6, s3, v6
	v_lshlrev_b32_e32 v98, 11, v6
	v_lshl_add_u64 v[6:7], v[8:9], 0, v[98:99]
	v_add_co_u32_e32 v6, vcc, 0x40000, v6
	s_nop 1
	v_addc_co_u32_e32 v7, vcc, 0, v7, vcc
	global_store_dwordx4 v[6:7], v[2:5], off sc1
	s_waitcnt lgkmcnt(0)

; #define LAS __attribute__((address_space(3)))
; __device__ __forceinline__ void xpose_item(const float* W, int K, int N, bf16* WT, const float* gain, int cmap, LAS float* scr, int item, int lane) {
;     ...
;     f32x4 w[16];
; #pragma unroll
;     for (int i = 0; i < 16; ++i) w[i] = __builtin_nontemporal_load((const f32x4*)(W + (size_t)(k0 + 4 * i + ks) * N + n0 + n4));
;     if (gain) {
; #pragma unroll
;         for (int i = 0; i < 16; ++i) w[i] = w[i] * gain[k0 + 4 * i + ks];
;     }
; #pragma unroll
;     for (int i = 0; i < 16; ++i) { LAS float* d = scr + (4 * i + ks) * XP_STRIDE + n4; d[0] = w[i][0]; d[1] = w[i][1]; d[2] = w[i][2]; d[3] = w[i][3]; }
; __device__ __forceinline__ void prologue(const Args& a, LAS unsigned char* lds, int vcu, int G, int wave, int lane, int tid) {
;     ...
;         if (r < I_SQ) { xpose_item(a.in[10], 1024, 1024, (bf16*)(ws + WS_WCO), nullptr, 4, scr, r, lane); continue; } r -= I_SQ;
.LBB0_541:
	s_andn2_b64 vcc, exec, s[4:5]
	s_cbranch_vccnz .LBB0_543
	s_add_i32 s3, s1, 0x300
	s_and_b32 s3, s3, 0x3c0
	s_and_b32 s4, s13, 0x3c0
	v_or_b32_e32 v4, s3, v67
	s_lshl_b32 s86, s4, 2
	v_lshl_add_u64 v[2:3], v[78:79], 0, s[86:87]
	v_lshlrev_b32_e32 v98, 12, v4
	v_lshl_add_u64 v[62:63], v[2:3], 0, v[98:99]
	v_add_co_u32_e32 v6, vcc, 0x4000, v62
	s_lshl_b32 s86, s3, 1
	s_nop 0
	v_addc_co_u32_e32 v7, vcc, 0, v63, vcc
	v_add_co_u32_e32 v10, vcc, 0x8000, v62
	global_load_dwordx4 v[2:5], v[62:63], off nt
	s_nop 0
	global_load_dwordx4 v[6:9], v[6:7], off nt
	v_addc_co_u32_e32 v11, vcc, 0, v63, vcc
	v_add_co_u32_e32 v14, vcc, 0xc000, v62
	s_and_b32 s3, s15, 0x60
	s_nop 0
	v_addc_co_u32_e32 v15, vcc, 0, v63, vcc
	global_load_dwordx4 v[10:13], v[10:11], off nt
	s_nop 0
	global_load_dwordx4 v[14:17], v[14:15], off nt
	v_add_co_u32_e32 v18, vcc, 0x10000, v62
	s_and_b32 s4, s13, 0x300
	s_nop 0
	v_addc_co_u32_e32 v19, vcc, 0, v63, vcc
	v_add_co_u32_e32 v22, vcc, 0x14000, v62
	s_or_b32 s4, s4, s3
	s_nop 0
	v_addc_co_u32_e32 v23, vcc, 0, v63, vcc
	global_load_dwordx4 v[18:21], v[18:19], off nt
	s_nop 0
	global_load_dwordx4 v[22:25], v[22:23], off nt
	v_add_co_u32_e32 v26, vcc, 0x18000, v62
	s_nop 1
	v_addc_co_u32_e32 v27, vcc, 0, v63, vcc
	v_add_co_u32_e32 v30, vcc, 0x1c000, v62
	s_nop 1
	v_addc_co_u32_e32 v31, vcc, 0, v63, vcc
	global_load_dwordx4 v[26:29], v[26:27], off nt
	s_nop 0
	global_load_dwordx4 v[30:33], v[30:31], off nt
	v_add_co_u32_e32 v34, vcc, 0x20000, v62
	s_nop 1
	v_addc_co_u32_e32 v35, vcc, 0, v63, vcc
	v_add_co_u32_e32 v38, vcc, 0x24000, v62
	s_nop 1
	v_addc_co_u32_e32 v39, vcc, 0, v63, vcc
	global_load_dwordx4 v[34:37], v[34:35], off nt
	s_nop 0
	global_load_dwordx4 v[38:41], v[38:39], off nt
	v_add_co_u32_e32 v42, vcc, 0x28000, v62
	s_nop 1
	v_addc_co_u32_e32 v43, vcc, 0, v63, vcc
	v_add_co_u32_e32 v46, vcc, 0x2c000, v62
	s_nop 1
	v_addc_co_u32_e32 v47, vcc, 0, v63, vcc
	global_load_dwordx4 v[42:45], v[42:43], off nt
	s_nop 0
	global_load_dwordx4 v[46:49], v[46:47], off nt
	v_add_co_u32_e32 v50, vcc, 0x30000, v62
	s_nop 1
	v_addc_co_u32_e32 v51, vcc, 0, v63, vcc
	v_add_co_u32_e32 v54, vcc, 0x34000, v62
	s_nop 1
	v_addc_co_u32_e32 v55, vcc, 0, v63, vcc
	global_load_dwordx4 v[50:53], v[50:51], off nt
	s_nop 0
	global_load_dwordx4 v[54:57], v[54:55], off nt
	v_add_co_u32_e32 v58, vcc, 0x38000, v62
	s_nop 1
	v_addc_co_u32_e32 v59, vcc, 0, v63, vcc
	global_load_dwordx4 v[58:61], v[58:59], off nt
	v_add_co_u32_e32 v62, vcc, 0x3c000, v62
	s_nop 1
	v_addc_co_u32_e32 v63, vcc, 0, v63, vcc
	global_load_dwordx4 v[62:65], v[62:63], off nt
	s_cselect_b32 s84, 1, 0
	s_cmp_eq_u32 s32, 1
	s_cbranch_scc1 .Lmy_yield_4
.Lmy_resume_4:
	s_cmp_lg_u32 s84, 0
	s_waitcnt vmcnt(15)
	ds_write2_b32 v69, v2, v3 offset1:1
	ds_write2_b32 v69, v4, v5 offset0:2 offset1:3
	v_add_u32_e32 v2, 0x410, v69
	s_waitcnt vmcnt(14)
	ds_write2_b32 v2, v6, v7 offset1:1
	v_add_u32_e32 v2, 0x418, v69
	ds_write2_b32 v2, v8, v9 offset1:1
	v_add_u32_e32 v2, 0x820, v69
	v_lshl_add_u64 v[8:9], v[74:75], 0, s[86:87]
	s_waitcnt vmcnt(13)
	ds_write2_b32 v2, v10, v11 offset1:1
	v_add_u32_e32 v2, 0x828, v69
	ds_write2_b32 v2, v12, v13 offset1:1
	v_add_u32_e32 v2, 0xc30, v69
	s_waitcnt vmcnt(12)
	ds_write2_b32 v2, v14, v15 offset1:1
	v_add_u32_e32 v2, 0xc38, v69
	ds_write2_b32 v2, v16, v17 offset1:1
	v_add_u32_e32 v2, 0x1040, v69
	v_add_u32_e32 v14, 0x400, v73
	v_or_b32_e32 v10, s4, v71
	v_lshlrev_b32_e32 v98, 11, v10
	s_waitcnt vmcnt(11)
	ds_write2_b32 v2, v18, v19 offset1:1
	v_add_u32_e32 v2, 0x1048, v69
	ds_write2_b32 v2, v20, v21 offset1:1
	v_add_u32_e32 v2, 0x1450, v69
	s_waitcnt vmcnt(10)
	ds_write2_b32 v2, v22, v23 offset1:1
	v_add_u32_e32 v2, 0x1458, v69
	ds_write2_b32 v2, v24, v25 offset1:1
	v_add_u32_e32 v2, 0x1860, v69
	v_lshl_add_u64 v[10:11], v[8:9], 0, v[98:99]
	v_or_b32_e32 v12, s4, v84
	v_lshlrev_b32_e32 v98, 11, v12
	s_waitcnt vmcnt(9)
	ds_write2_b32 v2, v26, v27 offset1:1
	v_add_u32_e32 v2, 0x1868, v69
	ds_write2_b32 v2, v28, v29 offset1:1
	v_add_u32_e32 v2, 0x1c70, v69
	s_waitcnt vmcnt(8)
	ds_write2_b32 v2, v30, v31 offset1:1
	v_add_u32_e32 v2, 0x1c78, v69
	ds_write2_b32 v2, v32, v33 offset1:1
	v_add_u32_e32 v2, 0x2080, v69
	v_lshl_add_u64 v[12:13], v[8:9], 0, v[98:99]
	s_waitcnt vmcnt(7)
	ds_write2_b32 v2, v34, v35 offset1:1
	v_add_u32_e32 v2, 0x2088, v69
	ds_write2_b32 v2, v36, v37 offset1:1
	v_add_u32_e32 v2, 0x2490, v69
	s_waitcnt vmcnt(6)
	ds_write2_b32 v2, v38, v39 offset1:1
	v_add_u32_e32 v2, 0x2498, v69
	ds_write2_b32 v2, v40, v41 offset1:1
	v_add_u32_e32 v2, 0x28a0, v69
	s_waitcnt vmcnt(5)
	ds_write2_b32 v2, v42, v43 offset1:1
	v_add_u32_e32 v2, 0x28a8, v69
	ds_write2_b32 v2, v44, v45 offset1:1
	v_add_u32_e32 v2, 0x2cb0, v69
	s_waitcnt vmcnt(4)
	ds_write2_b32 v2, v46, v47 offset1:1
	v_add_u32_e32 v2, 0x2cb8, v69
	ds_write2_b32 v2, v48, v49 offset1:1
	v_add_u32_e32 v2, 0x30c0, v69
	s_waitcnt vmcnt(3)
	ds_write2_b32 v2, v50, v51 offset1:1
	v_add_u32_e32 v2, 0x30c8, v69
	ds_write2_b32 v2, v52, v53 offset1:1
	v_add_u32_e32 v2, 0x34d0, v69
	s_waitcnt vmcnt(2)
; #define LAS __attribute__((address_space(3)))
; #define LDS_WAIT() asm volatile("s_waitcnt lgkmcnt(0)" ::: "memory")
; __device__ __forceinline__ unsigned pk2(float lo, float hi) { return pg8::cvt_pk_bf16(lo, hi); }
; __device__ __forceinline__ void xpose_item(const float* W, int K, int N, bf16* WT, const float* gain, int cmap, LAS float* scr, int item, int lane) {
;     ...
;     for (int i = 0; i < 16; ++i) { LAS float* d = scr + (4 * i + ks) * XP_STRIDE + n4; d[0] = w[i][0]; d[1] = w[i][1]; d[2] = w[i][2]; d[3] = w[i][3]; }
;     LDS_WAIT(); asm volatile("" ::: "memory");
;     int r0 = n0;
;     if (cmap == 1) { if (n0 < 1024) r0 = 2048 + n0; else if (n0 < 2048) { const int c = n0 - 1024; r0 = (c >> 7) * 256 + (c & 127); } else { const int c = n0 - 2048; r0 = (c >> 7) * 256 + 128 + (c & 127); } }
;     const int c = lane & 7;
; #pragma unroll
;     for (int j = 0; j < 8; ++j) { const int n = (lane >> 3) + 8 * j; const LAS float* sp = scr + (8 * c) * XP_STRIDE + n;
;         v4u o; o.x = pk2(sp[0 * XP_STRIDE], sp[1 * XP_STRIDE]); o.y = pk2(sp[2 * XP_STRIDE], sp[3 * XP_STRIDE]); o.z = pk2(sp[4 * XP_STRIDE], sp[5 * XP_STRIDE]); o.w = pk2(sp[6 * XP_STRIDE], sp[7 * XP_STRIDE]);
;         int rr = r0 + n;
;         if (cmap == 4) { const int cc = rr & 255; rr = (rr & ~255) + 128 * ((cc >> 5) & 1) + 32 * (cc >> 6) + (cc & 31); }
;         *(v4u*)(WT + (size_t)rr * K + k0 + 8 * c) = o; }
	ds_write2_b32 v2, v54, v55 offset1:1
	v_add_u32_e32 v2, 0x34d8, v69
	ds_write2_b32 v2, v56, v57 offset1:1
	v_add_u32_e32 v2, 0x38e0, v69
	s_waitcnt vmcnt(1)
	ds_write2_b32 v2, v58, v59 offset1:1
	v_add_u32_e32 v2, 0x38e8, v69
	ds_write2_b32 v2, v60, v61 offset1:1
	v_add_u32_e32 v2, 0x3cf0, v69
	s_waitcnt vmcnt(0)
	ds_write2_b32 v2, v62, v63 offset1:1
	v_add_u32_e32 v2, 0x3cf8, v69
	ds_write2_b32 v2, v64, v65 offset1:1
	s_waitcnt lgkmcnt(0)
	ds_read2_b32 v[2:3], v73 offset1:65
	s_waitcnt lgkmcnt(0)
	v_cvt_pk_bf16_f32 v2, v2, v3
	ds_read2_b32 v[4:5], v73 offset0:130 offset1:195
	s_waitcnt lgkmcnt(0)
	v_cvt_pk_bf16_f32 v3, v4, v5
	ds_read2_b32 v[4:5], v14 offset0:4 offset1:69
	s_waitcnt lgkmcnt(0)
	v_cvt_pk_bf16_f32 v4, v4, v5
	ds_read2_b32 v[6:7], v14 offset0:134 offset1:199
	s_waitcnt lgkmcnt(0)
	v_cvt_pk_bf16_f32 v5, v6, v7
	ds_read2_b32 v[6:7], v73 offset0:8 offset1:73
	global_store_dwordx4 v[10:11], v[2:5], off sc1
	s_waitcnt lgkmcnt(0)
	s_nop 0
	v_cvt_pk_bf16_f32 v2, v6, v7
	ds_read2_b32 v[4:5], v73 offset0:138 offset1:203
	s_waitcnt lgkmcnt(0)
	v_cvt_pk_bf16_f32 v3, v4, v5
	ds_read2_b32 v[4:5], v14 offset0:12 offset1:77
	s_waitcnt lgkmcnt(0)
	v_cvt_pk_bf16_f32 v4, v4, v5
	ds_read2_b32 v[6:7], v14 offset0:142 offset1:207
	s_waitcnt lgkmcnt(0)
	v_cvt_pk_bf16_f32 v5, v6, v7
	ds_read2_b32 v[6:7], v73 offset0:16 offset1:81
	global_store_dwordx4 v[12:13], v[2:5], off sc1
	v_or_b32_e32 v12, s4, v85
	v_lshlrev_b32_e32 v98, 11, v12
	s_waitcnt lgkmcnt(0)
	v_cvt_pk_bf16_f32 v2, v6, v7
	ds_read2_b32 v[4:5], v73 offset0:146 offset1:211
	s_waitcnt lgkmcnt(0)
	v_cvt_pk_bf16_f32 v3, v4, v5
	ds_read2_b32 v[4:5], v14 offset0:20 offset1:85
	s_waitcnt lgkmcnt(0)
	v_cvt_pk_bf16_f32 v4, v4, v5
	ds_read2_b32 v[6:7], v14 offset0:150 offset1:215
	s_waitcnt lgkmcnt(0)
	v_cvt_pk_bf16_f32 v5, v6, v7
	v_lshl_add_u64 v[12:13], v[8:9], 0, v[98:99]
	ds_read2_b32 v[6:7], v73 offset0:24 offset1:89
	global_store_dwordx4 v[12:13], v[2:5], off sc1
	v_or_b32_e32 v12, s4, v86
	v_lshlrev_b32_e32 v98, 11, v12
	s_waitcnt lgkmcnt(0)
	v_cvt_pk_bf16_f32 v2, v6, v7
	ds_read2_b32 v[4:5], v73 offset0:154 offset1:219
	s_waitcnt lgkmcnt(0)
	v_cvt_pk_bf16_f32 v3, v4, v5
	ds_read2_b32 v[4:5], v14 offset0:28 offset1:93
	s_waitcnt lgkmcnt(0)
	v_cvt_pk_bf16_f32 v4, v4, v5
	ds_read2_b32 v[6:7], v14 offset0:158 offset1:223
	s_waitcnt lgkmcnt(0)
	v_cvt_pk_bf16_f32 v5, v6, v7
	v_lshl_add_u64 v[12:13], v[8:9], 0, v[98:99]
	ds_read2_b32 v[6:7], v73 offset0:32 offset1:97
	global_store_dwordx4 v[12:13], v[2:5], off sc1
	s_mov_b32 s4, 0x40000
	v_add_co_u32_e32 v10, vcc, s4, v10
	s_waitcnt lgkmcnt(0)
	v_cvt_pk_bf16_f32 v2, v6, v7
	ds_read2_b32 v[4:5], v73 offset0:162 offset1:227
	s_waitcnt lgkmcnt(0)
	v_cvt_pk_bf16_f32 v3, v4, v5
	ds_read2_b32 v[4:5], v14 offset0:36 offset1:101
	s_waitcnt lgkmcnt(0)
	v_cvt_pk_bf16_f32 v4, v4, v5
	ds_read2_b32 v[6:7], v14 offset0:166 offset1:231
	s_waitcnt lgkmcnt(0)
	v_cvt_pk_bf16_f32 v5, v6, v7
	v_addc_co_u32_e32 v11, vcc, 0, v11, vcc
	ds_read2_b32 v[6:7], v73 offset0:40 offset1:105
	global_store_dwordx4 v[10:11], v[2:5], off sc1
	v_add_u32_e32 v12, s13, v71
	s_waitcnt lgkmcnt(0)
	v_cvt_pk_bf16_f32 v2, v6, v7
	ds_read2_b32 v[4:5], v73 offset0:170 offset1:235
	s_waitcnt lgkmcnt(0)
	v_cvt_pk_bf16_f32 v3, v4, v5
	ds_read2_b32 v[4:5], v14 offset0:44 offset1:109
	s_waitcnt lgkmcnt(0)
	v_cvt_pk_bf16_f32 v4, v4, v5
	ds_read2_b32 v[6:7], v14 offset0:174 offset1:239
	s_waitcnt lgkmcnt(0)
	v_cvt_pk_bf16_f32 v5, v6, v7
	v_add_u32_e32 v6, 40, v12
	v_and_b32_e32 v6, 0x30f, v6
	v_or_b32_e32 v6, s3, v6
	v_lshlrev_b32_e32 v98, 11, v6
	v_lshl_add_u64 v[6:7], v[8:9], 0, v[98:99]
	v_add_co_u32_e32 v6, vcc, s4, v6
	ds_read2_b32 v[10:11], v73 offset0:48 offset1:113
	s_nop 0
	v_addc_co_u32_e32 v7, vcc, 0, v7, vcc
	global_store_dwordx4 v[6:7], v[2:5], off sc1
	s_waitcnt lgkmcnt(0)
	s_nop 0
	v_cvt_pk_bf16_f32 v2, v10, v11
	ds_read2_b32 v[4:5], v73 offset0:178 offset1:243
	s_waitcnt lgkmcnt(0)
	v_cvt_pk_bf16_f32 v3, v4, v5
	ds_read2_b32 v[4:5], v14 offset0:52 offset1:117
	s_waitcnt lgkmcnt(0)
	v_cvt_pk_bf16_f32 v4, v4, v5
	ds_read2_b32 v[6:7], v14 offset0:182 offset1:247
	s_waitcnt lgkmcnt(0)
	v_cvt_pk_bf16_f32 v5, v6, v7
	v_add_u32_e32 v6, 48, v12
	v_and_b32_e32 v6, 0x317, v6
	v_or_b32_e32 v6, s3, v6
	v_lshlrev_b32_e32 v98, 11, v6
	v_lshl_add_u64 v[6:7], v[8:9], 0, v[98:99]
	v_add_co_u32_e32 v6, vcc, s4, v6
	ds_read2_b32 v[10:11], v73 offset0:56 offset1:121
	s_nop 0
	v_addc_co_u32_e32 v7, vcc, 0, v7, vcc
	global_store_dwordx4 v[6:7], v[2:5], off sc1
	s_waitcnt lgkmcnt(0)
	s_nop 0
	v_cvt_pk_bf16_f32 v2, v10, v11
	ds_read2_b32 v[4:5], v73 offset0:186 offset1:251
	s_waitcnt lgkmcnt(0)
	v_cvt_pk_bf16_f32 v3, v4, v5
	ds_read2_b32 v[4:5], v14 offset0:60 offset1:125
	s_waitcnt lgkmcnt(0)
	v_cvt_pk_bf16_f32 v4, v4, v5
	ds_read2_b32 v[6:7], v14 offset0:190 offset1:255
	s_waitcnt lgkmcnt(0)
	v_cvt_pk_bf16_f32 v5, v6, v7
	v_add_u32_e32 v6, 56, v12
	v_and_b32_e32 v6, 0x31f, v6
	v_or_b32_e32 v6, s3, v6
	v_lshlrev_b32_e32 v98, 11, v6
	v_lshl_add_u64 v[6:7], v[8:9], 0, v[98:99]
	v_add_co_u32_e32 v6, vcc, 0x40000, v6
	s_nop 1
	v_addc_co_u32_e32 v7, vcc, 0, v7, vcc
	global_store_dwordx4 v[6:7], v[2:5], off sc1
	s_waitcnt lgkmcnt(0)

; __device__ __forceinline__ void xpose_item(const float* W, int K, int N, bf16* WT, const float* gain, int cmap, LAS float* scr, int item, int lane) {
;     ...
;     f32x4 w[16];
; #pragma unroll
;     for (int i = 0; i < 16; ++i) w[i] = __builtin_nontemporal_load((const f32x4*)(W + (size_t)(k0 + 4 * i + ks) * N + n0 + n4));
;     if (gain) {
; #pragma unroll
;         for (int i = 0; i < 16; ++i) w[i] = w[i] * gain[k0 + 4 * i + ks];
; __device__ __forceinline__ void prologue(const Args& a, LAS unsigned char* lds, int vcu, int G, int wave, int lane, int tid) {
;     ...
;         if (r < I_QKV) { xpose_item(a.in[8], 1024, 3072, (bf16*)(ws + WS_WCI), nmix + 2 * 1024, 1, scr, r, lane); continue; } r -= I_QKV;
.LBB0_544:
	s_andn2_b64 vcc, exec, s[4:5]
	s_cbranch_vccnz .LBB0_554
	s_add_i32 s3, s2, 0xf7c0
	s_and_b32 s4, s3, 0xffff
	s_mul_i32 s4, s4, 0xaaab
	s_lshr_b32 s4, s4, 21
	s_mul_i32 s5, s4, 48
	s_sub_i32 s3, s3, s5
	s_and_b32 s9, s3, 0xffff
	s_lshl_b32 s3, s4, 6
	v_or_b32_e32 v82, s3, v67
	s_lshl_b32 s86, s9, 8
	v_lshl_add_u64 v[58:59], v[80:81], 0, s[86:87]
	v_or_b32_e32 v83, 4, v82
	v_or_b32_e32 v95, 8, v82
	v_or_b32_e32 v97, 12, v82
	v_or_b32_e32 v100, 16, v82
	v_or_b32_e32 v101, 20, v82
	v_or_b32_e32 v103, 24, v82
	v_or_b32_e32 v105, 28, v82
	v_or_b32_e32 v107, 32, v82
	v_or_b32_e32 v109, 36, v82
	v_or_b32_e32 v111, 40, v82
	v_or_b32_e32 v113, 44, v82
	v_or_b32_e32 v115, 48, v82
	v_or_b32_e32 v117, 52, v82
	v_or_b32_e32 v119, 56, v82
	v_or_b32_e32 v121, 60, v82
	v_mad_u64_u32 v[2:3], s[4:5], v82, s21, v[58:59]
	v_mad_u64_u32 v[6:7], s[4:5], v83, s21, v[58:59]
	v_mad_u64_u32 v[10:11], s[4:5], v95, s21, v[58:59]
	v_mad_u64_u32 v[14:15], s[4:5], v97, s21, v[58:59]
	v_mad_u64_u32 v[18:19], s[4:5], v100, s21, v[58:59]
	v_mad_u64_u32 v[22:23], s[4:5], v101, s21, v[58:59]
	v_mad_u64_u32 v[26:27], s[4:5], v103, s21, v[58:59]
	v_mad_u64_u32 v[30:31], s[4:5], v105, s21, v[58:59]
	v_mad_u64_u32 v[34:35], s[4:5], v107, s21, v[58:59]
	v_mad_u64_u32 v[38:39], s[4:5], v109, s21, v[58:59]
	v_mad_u64_u32 v[42:43], s[4:5], v111, s21, v[58:59]
	v_mad_u64_u32 v[46:47], s[4:5], v113, s21, v[58:59]
	v_mad_u64_u32 v[50:51], s[4:5], v115, s21, v[58:59]
	v_mad_u64_u32 v[54:55], s[4:5], v117, s21, v[58:59]
	v_mad_u64_u32 v[60:61], s[4:5], v119, s21, v[58:59]
	v_mad_u64_u32 v[62:63], s[4:5], v121, s21, v[58:59]
	v_readlane_b32 s4, v253, 11
	v_lshlrev_b32_e32 v82, 2, v82
	v_readlane_b32 s5, v253, 12
	global_load_dwordx4 v[2:5], v[2:3], off nt
	s_nop 0
	global_load_dwordx4 v[6:9], v[6:7], off nt
	s_nop 0
	global_load_dwordx4 v[10:13], v[10:11], off nt
	s_nop 0
	global_load_dwordx4 v[14:17], v[14:15], off nt
	s_nop 0
	global_load_dwordx4 v[18:21], v[18:19], off nt
	s_nop 0
	global_load_dwordx4 v[22:25], v[22:23], off nt
	s_nop 0
	global_load_dwordx4 v[26:29], v[26:27], off nt
	s_nop 0
	global_load_dwordx4 v[30:33], v[30:31], off nt
	s_nop 0
	global_load_dwordx4 v[34:37], v[34:35], off nt
	s_nop 0
	global_load_dwordx4 v[38:41], v[38:39], off nt
	s_nop 0
	global_load_dwordx4 v[42:45], v[42:43], off nt
	s_nop 0
	global_load_dwordx4 v[46:49], v[46:47], off nt
	s_nop 0
	global_load_dwordx4 v[50:53], v[50:51], off nt
	s_nop 0
	global_load_dwordx4 v[54:57], v[54:55], off nt
	s_nop 0
	global_load_dwordx4 v[58:61], v[60:61], off nt
	s_nop 0
	global_load_dwordx4 v[62:65], v[62:63], off nt
	v_lshlrev_b32_e32 v83, 2, v83
	global_load_dword v82, v82, s[4:5]
	s_lshl_b32 s10, s9, 6
	global_load_dword v94, v83, s[4:5]
	v_lshlrev_b32_e32 v83, 2, v95
	global_load_dword v96, v83, s[4:5]
	v_lshlrev_b32_e32 v83, 2, v97
	global_load_dword v98, v83, s[4:5]
	v_lshlrev_b32_e32 v83, 2, v100
	global_load_dword v100, v83, s[4:5]
	v_lshlrev_b32_e32 v83, 2, v101
	global_load_dword v102, v83, s[4:5]
	v_lshlrev_b32_e32 v83, 2, v103
	global_load_dword v104, v83, s[4:5]
	v_lshlrev_b32_e32 v83, 2, v105
	global_load_dword v106, v83, s[4:5]
	v_lshlrev_b32_e32 v83, 2, v107
	global_load_dword v108, v83, s[4:5]
	v_lshlrev_b32_e32 v83, 2, v109
	global_load_dword v110, v83, s[4:5]
	v_lshlrev_b32_e32 v83, 2, v111
	global_load_dword v112, v83, s[4:5]
	v_lshlrev_b32_e32 v83, 2, v113
	global_load_dword v114, v83, s[4:5]
	v_lshlrev_b32_e32 v83, 2, v115
	global_load_dword v116, v83, s[4:5]
	v_lshlrev_b32_e32 v83, 2, v117
	global_load_dword v118, v83, s[4:5]
	v_lshlrev_b32_e32 v83, 2, v119
	global_load_dword v120, v83, s[4:5]
	v_lshlrev_b32_e32 v83, 2, v121
	global_load_dword v122, v83, s[4:5]
	s_cmp_gt_u32 s9, 15
	s_mov_b64 s[4:5], -1
	s_cselect_b32 s84, 1, 0
	s_cmp_eq_u32 s32, 1
	s_cbranch_scc1 .Lmy_yield_5
; #define LAS __attribute__((address_space(3)))
; #define LDS_WAIT() asm volatile("s_waitcnt lgkmcnt(0)" ::: "memory")
; __device__ __forceinline__ void xpose_item(const float* W, int K, int N, bf16* WT, const float* gain, int cmap, LAS float* scr, int item, int lane) {
;     ...
;     if (gain) {
; #pragma unroll
;         for (int i = 0; i < 16; ++i) w[i] = w[i] * gain[k0 + 4 * i + ks];
;     }
; #pragma unroll
;     for (int i = 0; i < 16; ++i) { LAS float* d = scr + (4 * i + ks) * XP_STRIDE + n4; d[0] = w[i][0]; d[1] = w[i][1]; d[2] = w[i][2]; d[3] = w[i][3]; }
;     LDS_WAIT(); asm volatile("" ::: "memory");
;     int r0 = n0;
;     if (cmap == 1) { if (n0 < 1024) r0 = 2048 + n0; else if (n0 < 2048) { const int c = n0 - 1024; r0 = (c >> 7) * 256 + (c & 127); } else { const int c = n0 - 2048; r0 = (c >> 7) * 256 + 128 + (c & 127); } }
.Lmy_resume_5:
	s_cmp_lg_u32 s84, 0
	s_waitcnt vmcnt(15)
	v_pk_mul_f32 v[2:3], v[2:3], v[82:83] op_sel_hi:[1,0]
	v_pk_mul_f32 v[4:5], v[4:5], v[82:83] op_sel_hi:[1,0]
	s_waitcnt vmcnt(14)
	v_pk_mul_f32 v[6:7], v[6:7], v[94:95] op_sel_hi:[1,0]
	ds_write2_b32 v69, v2, v3 offset1:1
	ds_write2_b32 v69, v4, v5 offset0:2 offset1:3
	v_add_u32_e32 v2, 0x410, v69
	v_pk_mul_f32 v[8:9], v[8:9], v[94:95] op_sel_hi:[1,0]
	ds_write2_b32 v2, v6, v7 offset1:1
	v_add_u32_e32 v2, 0x418, v69
	s_waitcnt vmcnt(13)
	v_pk_mul_f32 v[10:11], v[10:11], v[96:97] op_sel_hi:[1,0]
	ds_write2_b32 v2, v8, v9 offset1:1
	v_add_u32_e32 v2, 0x820, v69
	v_pk_mul_f32 v[12:13], v[12:13], v[96:97] op_sel_hi:[1,0]
	ds_write2_b32 v2, v10, v11 offset1:1
	v_add_u32_e32 v2, 0x828, v69
	s_waitcnt vmcnt(12)
	v_pk_mul_f32 v[14:15], v[14:15], v[98:99] op_sel_hi:[1,0]
	ds_write2_b32 v2, v12, v13 offset1:1
	v_add_u32_e32 v2, 0xc30, v69
	v_pk_mul_f32 v[16:17], v[16:17], v[98:99] op_sel_hi:[1,0]
	ds_write2_b32 v2, v14, v15 offset1:1
	v_add_u32_e32 v2, 0xc38, v69
	s_waitcnt vmcnt(11)
	v_pk_mul_f32 v[18:19], v[18:19], v[100:101] op_sel_hi:[1,0]
	ds_write2_b32 v2, v16, v17 offset1:1
	v_add_u32_e32 v2, 0x1040, v69
	v_pk_mul_f32 v[20:21], v[20:21], v[100:101] op_sel_hi:[1,0]
	ds_write2_b32 v2, v18, v19 offset1:1
	v_add_u32_e32 v2, 0x1048, v69
	s_waitcnt vmcnt(10)
	v_pk_mul_f32 v[22:23], v[22:23], v[102:103] op_sel_hi:[1,0]
	ds_write2_b32 v2, v20, v21 offset1:1
	v_add_u32_e32 v2, 0x1450, v69
	v_pk_mul_f32 v[24:25], v[24:25], v[102:103] op_sel_hi:[1,0]
	ds_write2_b32 v2, v22, v23 offset1:1
	v_add_u32_e32 v2, 0x1458, v69
	s_waitcnt vmcnt(9)
	v_pk_mul_f32 v[26:27], v[26:27], v[104:105] op_sel_hi:[1,0]
	ds_write2_b32 v2, v24, v25 offset1:1
	v_add_u32_e32 v2, 0x1860, v69
	v_pk_mul_f32 v[28:29], v[28:29], v[104:105] op_sel_hi:[1,0]
	ds_write2_b32 v2, v26, v27 offset1:1
	v_add_u32_e32 v2, 0x1868, v69
	s_waitcnt vmcnt(8)
	v_pk_mul_f32 v[30:31], v[30:31], v[106:107] op_sel_hi:[1,0]
	ds_write2_b32 v2, v28, v29 offset1:1
	v_add_u32_e32 v2, 0x1c70, v69
	v_pk_mul_f32 v[32:33], v[32:33], v[106:107] op_sel_hi:[1,0]
	ds_write2_b32 v2, v30, v31 offset1:1
	v_add_u32_e32 v2, 0x1c78, v69
	s_waitcnt vmcnt(7)
	v_pk_mul_f32 v[34:35], v[34:35], v[108:109] op_sel_hi:[1,0]
	ds_write2_b32 v2, v32, v33 offset1:1
	v_add_u32_e32 v2, 0x2080, v69
	v_pk_mul_f32 v[36:37], v[36:37], v[108:109] op_sel_hi:[1,0]
	ds_write2_b32 v2, v34, v35 offset1:1
	v_add_u32_e32 v2, 0x2088, v69
	s_waitcnt vmcnt(6)
	v_pk_mul_f32 v[38:39], v[38:39], v[110:111] op_sel_hi:[1,0]
	ds_write2_b32 v2, v36, v37 offset1:1
	v_add_u32_e32 v2, 0x2490, v69
	v_pk_mul_f32 v[40:41], v[40:41], v[110:111] op_sel_hi:[1,0]
	ds_write2_b32 v2, v38, v39 offset1:1
	v_add_u32_e32 v2, 0x2498, v69
	s_waitcnt vmcnt(5)
	v_pk_mul_f32 v[42:43], v[42:43], v[112:113] op_sel_hi:[1,0]
	ds_write2_b32 v2, v40, v41 offset1:1
	v_add_u32_e32 v2, 0x28a0, v69
	v_pk_mul_f32 v[44:45], v[44:45], v[112:113] op_sel_hi:[1,0]
	ds_write2_b32 v2, v42, v43 offset1:1
	v_add_u32_e32 v2, 0x28a8, v69
	s_waitcnt vmcnt(4)
	v_pk_mul_f32 v[46:47], v[46:47], v[114:115] op_sel_hi:[1,0]
	ds_write2_b32 v2, v44, v45 offset1:1
	v_add_u32_e32 v2, 0x2cb0, v69
	v_pk_mul_f32 v[48:49], v[48:49], v[114:115] op_sel_hi:[1,0]
	ds_write2_b32 v2, v46, v47 offset1:1
	v_add_u32_e32 v2, 0x2cb8, v69
	s_waitcnt vmcnt(3)
	v_pk_mul_f32 v[50:51], v[50:51], v[116:117] op_sel_hi:[1,0]
	ds_write2_b32 v2, v48, v49 offset1:1
	v_add_u32_e32 v2, 0x30c0, v69
	v_pk_mul_f32 v[52:53], v[52:53], v[116:117] op_sel_hi:[1,0]
	ds_write2_b32 v2, v50, v51 offset1:1
	v_add_u32_e32 v2, 0x30c8, v69
	s_waitcnt vmcnt(2)
	v_pk_mul_f32 v[54:55], v[54:55], v[118:119] op_sel_hi:[1,0]
	ds_write2_b32 v2, v52, v53 offset1:1
	v_add_u32_e32 v2, 0x34d0, v69
	v_pk_mul_f32 v[56:57], v[56:57], v[118:119] op_sel_hi:[1,0]
	ds_write2_b32 v2, v54, v55 offset1:1
	v_add_u32_e32 v2, 0x34d8, v69
	s_waitcnt vmcnt(1)
	v_pk_mul_f32 v[58:59], v[58:59], v[120:121] op_sel_hi:[1,0]
	ds_write2_b32 v2, v56, v57 offset1:1
	v_add_u32_e32 v2, 0x38e0, v69
	v_pk_mul_f32 v[60:61], v[60:61], v[120:121] op_sel_hi:[1,0]
	ds_write2_b32 v2, v58, v59 offset1:1
	v_add_u32_e32 v2, 0x38e8, v69
	s_waitcnt vmcnt(0)
	v_pk_mul_f32 v[62:63], v[62:63], v[122:123] op_sel_hi:[1,0]
	ds_write2_b32 v2, v60, v61 offset1:1
	v_add_u32_e32 v2, 0x3cf0, v69
	v_pk_mul_f32 v[64:65], v[64:65], v[122:123] op_sel_hi:[1,0]
	ds_write2_b32 v2, v62, v63 offset1:1
	v_add_u32_e32 v2, 0x3cf8, v69
	ds_write2_b32 v2, v64, v65 offset1:1
	s_waitcnt lgkmcnt(0)
	s_cbranch_scc0 .LBB0_551
	s_lshl_b32 s19, s9, 7
	s_and_b32 s11, s10, 64
	s_cmp_gt_u32 s9, 31
	s_cbranch_scc0 .LBB0_548
	s_or_b32 s4, s19, 0x80
	s_add_i32 s4, s4, s11
	s_add_i32 s8, s4, 0xfffff000
	s_mov_b64 s[4:5], 0

; __device__ __forceinline__ void xpose_item(const float* W, int K, int N, bf16* WT, const float* gain, int cmap, LAS float* scr, int item, int lane) {
;     ...
;     f32x4 w[16];
; #pragma unroll
;     for (int i = 0; i < 16; ++i) w[i] = __builtin_nontemporal_load((const f32x4*)(W + (size_t)(k0 + 4 * i + ks) * N + n0 + n4));
; __device__ __forceinline__ void prologue(const Args& a, LAS unsigned char* lds, int vcu, int G, int wave, int lane, int tid) {
;     ...
;         if (r < 4 * I_POOL) { const int g = r / I_POOL; r -= g * I_POOL; xpose_item(a.in[6] + (size_t)g * 65536, 256, 256, (bf16*)(ws + WS_WPOOL) + (size_t)g * 65536, nullptr, 4, scr, r, lane); continue; } r -= 4 * I_POOL;
.LBB0_555:
	s_andn2_b64 vcc, exec, s[4:5]
	s_cbranch_vccnz .LBB0_557
	s_add_i32 s3, s7, 0x1440
	s_lshr_b32 s86, s3, 4
	v_readlane_b32 s68, v253, 18
	s_lshl_b64 s[4:5], s[86:87], 18
	v_readlane_b32 s80, v253, 30
	v_readlane_b32 s81, v253, 31
	s_add_u32 s3, s80, s4
	s_addc_u32 s8, s81, s5
	s_lshl_b64 s[4:5], s[86:87], 17
	v_readlane_b32 s10, v253, 13
	v_readlane_b32 s11, v253, 14
	s_add_u32 s9, s10, s4
	s_addc_u32 s10, s11, s5
	s_and_b32 s4, s13, 0xc0
	s_and_b32 s11, s17, 0xc0
	s_lshl_b32 s4, s4, 2
	s_add_u32 s4, s3, s4
	v_or_b32_e32 v4, s11, v67
	s_addc_u32 s5, s8, 0
	v_lshlrev_b32_e32 v98, 2, v70
	v_lshl_add_u64 v[2:3], s[4:5], 0, v[98:99]
	v_lshlrev_b32_e32 v98, 10, v4
	v_lshl_add_u64 v[62:63], v[2:3], 0, v[98:99]
	s_movk_i32 s3, 0x2000
	v_add_co_u32_e32 v10, vcc, s3, v62
	s_movk_i32 s3, 0x4000
	s_nop 0
	v_addc_co_u32_e32 v11, vcc, 0, v63, vcc
	v_add_co_u32_e32 v18, vcc, s3, v62
	s_movk_i32 s3, 0x6000
	s_nop 0
	v_addc_co_u32_e32 v19, vcc, 0, v63, vcc
	v_add_co_u32_e32 v26, vcc, s3, v62
	s_mov_b32 s3, 0x8000
	s_nop 0
	v_addc_co_u32_e32 v27, vcc, 0, v63, vcc
	v_add_co_u32_e32 v34, vcc, s3, v62
	global_load_dwordx4 v[2:5], v[62:63], off nt
	global_load_dwordx4 v[6:9], v[10:11], off offset:-4096 nt
	s_nop 0
	global_load_dwordx4 v[10:13], v[10:11], off nt
	s_nop 0
	global_load_dwordx4 v[14:17], v[18:19], off offset:-4096 nt
	s_nop 0
	global_load_dwordx4 v[18:21], v[18:19], off nt
	s_nop 0
	global_load_dwordx4 v[22:25], v[26:27], off offset:-4096 nt
	s_nop 0
	global_load_dwordx4 v[26:29], v[26:27], off nt
	v_addc_co_u32_e32 v35, vcc, 0, v63, vcc
	global_load_dwordx4 v[30:33], v[34:35], off offset:-4096 nt
	s_nop 0
	global_load_dwordx4 v[34:37], v[34:35], off nt
	s_mov_b32 s3, 0xa000
	v_add_co_u32_e32 v42, vcc, s3, v62
	s_mov_b32 s3, 0xc000
	s_nop 0
	v_addc_co_u32_e32 v43, vcc, 0, v63, vcc
	global_load_dwordx4 v[38:41], v[42:43], off offset:-4096 nt
	s_nop 0
	global_load_dwordx4 v[42:45], v[42:43], off nt
	v_add_co_u32_e32 v50, vcc, s3, v62
	s_mov_b32 s3, 0xe000
	s_nop 0
	v_addc_co_u32_e32 v51, vcc, 0, v63, vcc
	global_load_dwordx4 v[46:49], v[50:51], off offset:-4096 nt
	s_nop 0
	global_load_dwordx4 v[50:53], v[50:51], off nt
	v_add_co_u32_e32 v58, vcc, s3, v62
	s_mov_b32 s3, 0xf000
	s_nop 0
	v_addc_co_u32_e32 v59, vcc, 0, v63, vcc
	global_load_dwordx4 v[54:57], v[58:59], off offset:-4096 nt
	s_nop 0
	global_load_dwordx4 v[58:61], v[58:59], off nt
	v_add_co_u32_e32 v62, vcc, s3, v62
	v_add_u32_e32 v82, 0x410, v69
	s_nop 0
	v_addc_co_u32_e32 v63, vcc, 0, v63, vcc
	global_load_dwordx4 v[62:65], v[62:63], off nt
	v_add_u32_e32 v83, 0x418, v69
	v_add_u32_e32 v94, 0x820, v69
	v_add_u32_e32 v95, 0x828, v69
	v_add_u32_e32 v96, 0xc30, v69
	v_add_u32_e32 v97, 0xc38, v69
	v_add_u32_e32 v98, 0x1040, v69
	v_add_u32_e32 v100, 0x1048, v69
	v_add_u32_e32 v101, 0x1450, v69
	v_add_u32_e32 v102, 0x1458, v69
	v_add_u32_e32 v103, 0x1860, v69
	v_add_u32_e32 v104, 0x1868, v69
	v_add_u32_e32 v105, 0x1c70, v69
	s_lshl_b32 s3, s11, 1
	s_add_u32 s4, s9, s3
	s_addc_u32 s5, s10, 0
	s_and_b32 s3, s15, 0x60
	v_readlane_b32 s69, v253, 19
	v_readlane_b32 s70, v253, 20
	v_readlane_b32 s71, v253, 21
	v_readlane_b32 s72, v253, 22
	v_readlane_b32 s73, v253, 23
	v_readlane_b32 s74, v253, 24
	v_readlane_b32 s75, v253, 25
	v_readlane_b32 s76, v253, 26
	v_readlane_b32 s77, v253, 27
	v_readlane_b32 s78, v253, 28
	s_cselect_b32 s84, 1, 0
	s_cmp_eq_u32 s32, 1
	s_cbranch_scc1 .Lmy_yield_6
; #define LAS __attribute__((address_space(3)))
; #define LDS_WAIT() asm volatile("s_waitcnt lgkmcnt(0)" ::: "memory")
; __device__ __forceinline__ unsigned pk2(float lo, float hi) { return pg8::cvt_pk_bf16(lo, hi); }
; __device__ __forceinline__ void xpose_item(const float* W, int K, int N, bf16* WT, const float* gain, int cmap, LAS float* scr, int item, int lane) {
;     ...
;     for (int i = 0; i < 16; ++i) { LAS float* d = scr + (4 * i + ks) * XP_STRIDE + n4; d[0] = w[i][0]; d[1] = w[i][1]; d[2] = w[i][2]; d[3] = w[i][3]; }
;     LDS_WAIT(); asm volatile("" ::: "memory");
;     int r0 = n0;
;     if (cmap == 1) { if (n0 < 1024) r0 = 2048 + n0; else if (n0 < 2048) { const int c = n0 - 1024; r0 = (c >> 7) * 256 + (c & 127); } else { const int c = n0 - 2048; r0 = (c >> 7) * 256 + 128 + (c & 127); } }
;     const int c = lane & 7;
; #pragma unroll
;     for (int j = 0; j < 8; ++j) { const int n = (lane >> 3) + 8 * j; const LAS float* sp = scr + (8 * c) * XP_STRIDE + n;
;         v4u o; o.x = pk2(sp[0 * XP_STRIDE], sp[1 * XP_STRIDE]); o.y = pk2(sp[2 * XP_STRIDE], sp[3 * XP_STRIDE]); o.z = pk2(sp[4 * XP_STRIDE], sp[5 * XP_STRIDE]); o.w = pk2(sp[6 * XP_STRIDE], sp[7 * XP_STRIDE]);
;         int rr = r0 + n;
;         if (cmap == 4) { const int cc = rr & 255; rr = (rr & ~255) + 128 * ((cc >> 5) & 1) + 32 * (cc >> 6) + (cc & 31); }
;         *(v4u*)(WT + (size_t)rr * K + k0 + 8 * c) = o; }
.Lmy_resume_6:
	s_cmp_lg_u32 s84, 0
	s_waitcnt vmcnt(15)
	ds_write2_b32 v69, v2, v3 offset1:1
	ds_write2_b32 v69, v4, v5 offset0:2 offset1:3
	s_waitcnt vmcnt(14)
	ds_write2_b32 v82, v6, v7 offset1:1
	ds_write2_b32 v83, v8, v9 offset1:1
	s_waitcnt vmcnt(13)
	ds_write2_b32 v94, v10, v11 offset1:1
	ds_write2_b32 v95, v12, v13 offset1:1
	s_waitcnt vmcnt(12)
	ds_write2_b32 v96, v14, v15 offset1:1
	ds_write2_b32 v97, v16, v17 offset1:1
	s_waitcnt vmcnt(11)
	ds_write2_b32 v98, v18, v19 offset1:1
	ds_write2_b32 v100, v20, v21 offset1:1
	s_waitcnt vmcnt(10)
	ds_write2_b32 v101, v22, v23 offset1:1
	ds_write2_b32 v102, v24, v25 offset1:1
	s_waitcnt vmcnt(9)
	ds_write2_b32 v103, v26, v27 offset1:1
	ds_write2_b32 v104, v28, v29 offset1:1
	s_waitcnt vmcnt(8)
	ds_write2_b32 v105, v30, v31 offset1:1
	v_add_u32_e32 v2, 0x1c78, v69
	ds_write2_b32 v2, v32, v33 offset1:1
	v_add_u32_e32 v2, 0x2080, v69
	s_waitcnt vmcnt(7)
	ds_write2_b32 v2, v34, v35 offset1:1
	v_add_u32_e32 v2, 0x2088, v69
	ds_write2_b32 v2, v36, v37 offset1:1
	v_add_u32_e32 v2, 0x2490, v69
	s_waitcnt vmcnt(6)
	ds_write2_b32 v2, v38, v39 offset1:1
	v_add_u32_e32 v2, 0x2498, v69
	ds_write2_b32 v2, v40, v41 offset1:1
	v_add_u32_e32 v2, 0x28a0, v69
	s_waitcnt vmcnt(5)
	ds_write2_b32 v2, v42, v43 offset1:1
	v_add_u32_e32 v2, 0x28a8, v69
	ds_write2_b32 v2, v44, v45 offset1:1
	v_add_u32_e32 v2, 0x2cb0, v69
	s_waitcnt vmcnt(4)
	ds_write2_b32 v2, v46, v47 offset1:1
	v_add_u32_e32 v2, 0x2cb8, v69
	ds_write2_b32 v2, v48, v49 offset1:1
	v_add_u32_e32 v2, 0x30c0, v69
	s_waitcnt vmcnt(3)
	ds_write2_b32 v2, v50, v51 offset1:1
	v_add_u32_e32 v2, 0x30c8, v69
	ds_write2_b32 v2, v52, v53 offset1:1
	v_add_u32_e32 v2, 0x34d0, v69
	s_waitcnt vmcnt(2)
	ds_write2_b32 v2, v54, v55 offset1:1
	v_add_u32_e32 v2, 0x34d8, v69
	ds_write2_b32 v2, v56, v57 offset1:1
	v_add_u32_e32 v2, 0x38e0, v69
	s_waitcnt vmcnt(1)
	ds_write2_b32 v2, v58, v59 offset1:1
	v_add_u32_e32 v2, 0x38e8, v69
	ds_write2_b32 v2, v60, v61 offset1:1
	v_add_u32_e32 v2, 0x3cf0, v69
	s_waitcnt vmcnt(0)
	ds_write2_b32 v2, v62, v63 offset1:1
	v_add_u32_e32 v2, 0x3cf8, v69
	ds_write2_b32 v2, v64, v65 offset1:1
	s_waitcnt lgkmcnt(0)
	ds_read2_b32 v[2:3], v73 offset1:65
	s_waitcnt lgkmcnt(0)
	v_cvt_pk_bf16_f32 v2, v2, v3
	ds_read2_b32 v[4:5], v73 offset0:130 offset1:195
	v_add_u32_e32 v14, 0x400, v73
	v_lshlrev_b32_e32 v98, 1, v72
	v_or_b32_e32 v10, s3, v71
	s_waitcnt lgkmcnt(0)
	v_cvt_pk_bf16_f32 v3, v4, v5
	ds_read2_b32 v[4:5], v14 offset0:4 offset1:69
	v_lshl_add_u64 v[8:9], s[4:5], 0, v[98:99]
	v_lshlrev_b32_e32 v98, 9, v10
	s_waitcnt lgkmcnt(0)
	v_cvt_pk_bf16_f32 v4, v4, v5
	ds_read2_b32 v[6:7], v14 offset0:134 offset1:199
	s_waitcnt lgkmcnt(0)
	v_cvt_pk_bf16_f32 v5, v6, v7
	v_lshl_add_u64 v[10:11], v[8:9], 0, v[98:99]
	ds_read2_b32 v[6:7], v73 offset0:8 offset1:73
	global_store_dwordx4 v[10:11], v[2:5], off sc1
	v_or_b32_e32 v12, s3, v84
	v_lshlrev_b32_e32 v98, 9, v12
	s_waitcnt lgkmcnt(0)
	v_cvt_pk_bf16_f32 v2, v6, v7
	ds_read2_b32 v[4:5], v73 offset0:138 offset1:203
	s_waitcnt lgkmcnt(0)
	v_cvt_pk_bf16_f32 v3, v4, v5
	ds_read2_b32 v[4:5], v14 offset0:12 offset1:77
	s_waitcnt lgkmcnt(0)
	v_cvt_pk_bf16_f32 v4, v4, v5
	ds_read2_b32 v[6:7], v14 offset0:142 offset1:207
	s_waitcnt lgkmcnt(0)
	v_cvt_pk_bf16_f32 v5, v6, v7
	v_lshl_add_u64 v[12:13], v[8:9], 0, v[98:99]
	ds_read2_b32 v[6:7], v73 offset0:16 offset1:81
	global_store_dwordx4 v[12:13], v[2:5], off sc1
	v_or_b32_e32 v12, s3, v85
	v_lshlrev_b32_e32 v98, 9, v12
	s_waitcnt lgkmcnt(0)
	v_cvt_pk_bf16_f32 v2, v6, v7
	ds_read2_b32 v[4:5], v73 offset0:146 offset1:211
	s_waitcnt lgkmcnt(0)
	v_cvt_pk_bf16_f32 v3, v4, v5
	ds_read2_b32 v[4:5], v14 offset0:20 offset1:85
	s_waitcnt lgkmcnt(0)
	v_cvt_pk_bf16_f32 v4, v4, v5
	ds_read2_b32 v[6:7], v14 offset0:150 offset1:215
	s_waitcnt lgkmcnt(0)
	v_cvt_pk_bf16_f32 v5, v6, v7
	v_lshl_add_u64 v[12:13], v[8:9], 0, v[98:99]
	ds_read2_b32 v[6:7], v73 offset0:24 offset1:89
	global_store_dwordx4 v[12:13], v[2:5], off sc1
	v_or_b32_e32 v12, s3, v86
	v_lshlrev_b32_e32 v98, 9, v12
	s_waitcnt lgkmcnt(0)
	v_cvt_pk_bf16_f32 v2, v6, v7
	ds_read2_b32 v[4:5], v73 offset0:154 offset1:219
	s_waitcnt lgkmcnt(0)
	v_cvt_pk_bf16_f32 v3, v4, v5
	ds_read2_b32 v[4:5], v14 offset0:28 offset1:93
	s_waitcnt lgkmcnt(0)
	v_cvt_pk_bf16_f32 v4, v4, v5
	ds_read2_b32 v[6:7], v14 offset0:158 offset1:223
	s_waitcnt lgkmcnt(0)
	v_cvt_pk_bf16_f32 v5, v6, v7
	v_lshl_add_u64 v[12:13], v[8:9], 0, v[98:99]
	ds_read2_b32 v[6:7], v73 offset0:32 offset1:97
	global_store_dwordx4 v[12:13], v[2:5], off sc1
	s_mov_b32 s4, 0x10000
	v_add_co_u32_e32 v10, vcc, s4, v10
	s_waitcnt lgkmcnt(0)
	v_cvt_pk_bf16_f32 v2, v6, v7
	ds_read2_b32 v[4:5], v73 offset0:162 offset1:227
	s_waitcnt lgkmcnt(0)
	v_cvt_pk_bf16_f32 v3, v4, v5
	ds_read2_b32 v[4:5], v14 offset0:36 offset1:101
	s_waitcnt lgkmcnt(0)
	v_cvt_pk_bf16_f32 v4, v4, v5
	ds_read2_b32 v[6:7], v14 offset0:166 offset1:231
	s_waitcnt lgkmcnt(0)
	v_cvt_pk_bf16_f32 v5, v6, v7
	v_addc_co_u32_e32 v11, vcc, 0, v11, vcc
	ds_read2_b32 v[6:7], v73 offset0:40 offset1:105
	global_store_dwordx4 v[10:11], v[2:5], off sc1
	v_readlane_b32 s79, v253, 29
	v_readlane_b32 s82, v253, 32
	s_waitcnt lgkmcnt(0)
	v_cvt_pk_bf16_f32 v2, v6, v7
	ds_read2_b32 v[4:5], v73 offset0:170 offset1:235
	s_waitcnt lgkmcnt(0)
	v_cvt_pk_bf16_f32 v3, v4, v5
	ds_read2_b32 v[4:5], v14 offset0:44 offset1:109
	s_waitcnt lgkmcnt(0)
	v_cvt_pk_bf16_f32 v4, v4, v5
	v_or_b32_e32 v5, s3, v91
	v_lshlrev_b32_e32 v98, 9, v5
	v_lshl_add_u64 v[10:11], v[8:9], 0, v[98:99]
	v_add_co_u32_e32 v10, vcc, s4, v10
	ds_read2_b32 v[6:7], v14 offset0:174 offset1:239
	s_waitcnt lgkmcnt(0)
	v_cvt_pk_bf16_f32 v5, v6, v7
	v_addc_co_u32_e32 v11, vcc, 0, v11, vcc
	ds_read2_b32 v[6:7], v73 offset0:48 offset1:113
	global_store_dwordx4 v[10:11], v[2:5], off sc1
	v_readlane_b32 s83, v253, 33
	s_waitcnt lgkmcnt(0)
	v_cvt_pk_bf16_f32 v2, v6, v7
	ds_read2_b32 v[4:5], v73 offset0:178 offset1:243
	s_waitcnt lgkmcnt(0)
	v_cvt_pk_bf16_f32 v3, v4, v5
	ds_read2_b32 v[4:5], v14 offset0:52 offset1:117
	s_waitcnt lgkmcnt(0)
	v_cvt_pk_bf16_f32 v4, v4, v5
	v_or_b32_e32 v5, s3, v92
	v_lshlrev_b32_e32 v98, 9, v5
	v_lshl_add_u64 v[10:11], v[8:9], 0, v[98:99]
	v_add_co_u32_e32 v10, vcc, s4, v10
	ds_read2_b32 v[6:7], v14 offset0:182 offset1:247
	s_nop 0
	v_addc_co_u32_e32 v11, vcc, 0, v11, vcc
	s_waitcnt lgkmcnt(0)
	v_cvt_pk_bf16_f32 v5, v6, v7
	global_store_dwordx4 v[10:11], v[2:5], off sc1
	v_or_b32_e32 v10, s3, v93
	v_lshlrev_b32_e32 v98, 9, v10
	v_lshl_add_u64 v[8:9], v[8:9], 0, v[98:99]
	ds_read2_b32 v[6:7], v73 offset0:56 offset1:121
	s_waitcnt lgkmcnt(0)
	v_cvt_pk_bf16_f32 v2, v6, v7
	ds_read2_b32 v[4:5], v73 offset0:186 offset1:251
	v_add_co_u32_e32 v8, vcc, 0x10000, v8
	s_waitcnt lgkmcnt(0)
	v_cvt_pk_bf16_f32 v3, v4, v5
	ds_read2_b32 v[4:5], v14 offset0:60 offset1:125
	v_addc_co_u32_e32 v9, vcc, 0, v9, vcc
	s_waitcnt lgkmcnt(0)
	v_cvt_pk_bf16_f32 v4, v4, v5
	ds_read2_b32 v[6:7], v14 offset0:190 offset1:255
	s_waitcnt lgkmcnt(0)
	v_cvt_pk_bf16_f32 v5, v6, v7
	global_store_dwordx4 v[8:9], v[2:5], off sc1
	s_waitcnt lgkmcnt(0)

; #define LAS __attribute__((address_space(3)))
; __device__ __forceinline__ void xpose_item(const float* W, int K, int N, bf16* WT, const float* gain, int cmap, LAS float* scr, int item, int lane) {
;     ...
;     f32x4 w[16];
; #pragma unroll
;     for (int i = 0; i < 16; ++i) w[i] = __builtin_nontemporal_load((const f32x4*)(W + (size_t)(k0 + 4 * i + ks) * N + n0 + n4));
;     if (gain) {
; #pragma unroll
;         for (int i = 0; i < 16; ++i) w[i] = w[i] * gain[k0 + 4 * i + ks];
;     }
; #pragma unroll
;     for (int i = 0; i < 16; ++i) { LAS float* d = scr + (4 * i + ks) * XP_STRIDE + n4; d[0] = w[i][0]; d[1] = w[i][1]; d[2] = w[i][2]; d[3] = w[i][3]; }
; __device__ __forceinline__ void prologue(const Args& a, LAS unsigned char* lds, int vcu, int G, int wave, int lane, int tid) {
;     ...
;         if (r < 2 * I_SQ) { const int l = r / I_SQ; r -= l * I_SQ; xpose_item(a.in[5] + (size_t)l * 1024 * 1024, 1024, 1024, (bf16*)(ws + WS_WO) + (size_t)l * 1024 * 1024, nullptr, 4, scr, r, lane); continue; } r -= 2 * I_SQ;
.LBB0_558:
	s_andn2_b64 vcc, exec, s[4:5]
	s_cbranch_vccnz .LBB0_560
	s_add_i32 s3, s7, 0x1640
	s_lshr_b32 s86, s3, 8
	v_readlane_b32 s68, v253, 18
	s_lshl_b64 s[4:5], s[86:87], 22
	v_readlane_b32 s78, v253, 28
	v_readlane_b32 s79, v253, 29
	s_add_u32 s3, s78, s4
	s_addc_u32 s8, s79, s5
	s_lshl_b64 s[4:5], s[86:87], 21
	s_add_u32 s9, s28, s4
	v_readlane_b32 s4, v253, 15
	s_addc_u32 s10, s4, s5
	s_and_b32 s4, s13, 0x3c0
	s_and_b32 s11, s1, 0x3c0
	s_lshl_b32 s4, s4, 2
	s_add_u32 s4, s3, s4
	v_or_b32_e32 v4, s11, v67
	s_addc_u32 s5, s8, 0
	v_lshlrev_b32_e32 v98, 2, v70
	v_lshl_add_u64 v[2:3], s[4:5], 0, v[98:99]
	v_lshlrev_b32_e32 v98, 12, v4
	v_lshl_add_u64 v[62:63], v[2:3], 0, v[98:99]
	s_movk_i32 s3, 0x4000
	v_add_co_u32_e32 v6, vcc, s3, v62
	s_mov_b32 s3, 0x8000
	s_nop 0
	v_addc_co_u32_e32 v7, vcc, 0, v63, vcc
	v_add_co_u32_e32 v10, vcc, s3, v62
	global_load_dwordx4 v[2:5], v[62:63], off nt
	s_nop 0
	global_load_dwordx4 v[6:9], v[6:7], off nt
	v_addc_co_u32_e32 v11, vcc, 0, v63, vcc
	s_mov_b32 s3, 0xc000
	v_add_co_u32_e32 v14, vcc, s3, v62
	s_mov_b32 s3, 0x10000
	s_nop 0
	v_addc_co_u32_e32 v15, vcc, 0, v63, vcc
	global_load_dwordx4 v[10:13], v[10:11], off nt
	s_nop 0
	global_load_dwordx4 v[14:17], v[14:15], off nt
	v_add_co_u32_e32 v18, vcc, s3, v62
	s_mov_b32 s3, 0x14000
	s_nop 0
	v_addc_co_u32_e32 v19, vcc, 0, v63, vcc
	v_add_co_u32_e32 v22, vcc, s3, v62
	s_mov_b32 s3, 0x18000
	s_nop 0
	v_addc_co_u32_e32 v23, vcc, 0, v63, vcc
	global_load_dwordx4 v[18:21], v[18:19], off nt
	s_nop 0
	global_load_dwordx4 v[22:25], v[22:23], off nt
	v_add_co_u32_e32 v26, vcc, s3, v62
	s_mov_b32 s3, 0x1c000
	s_nop 0
	v_addc_co_u32_e32 v27, vcc, 0, v63, vcc
	v_add_co_u32_e32 v30, vcc, s3, v62
	s_mov_b32 s3, 0x20000
	s_nop 0
	v_addc_co_u32_e32 v31, vcc, 0, v63, vcc
	global_load_dwordx4 v[26:29], v[26:27], off nt
	s_nop 0
	global_load_dwordx4 v[30:33], v[30:31], off nt
	v_add_co_u32_e32 v34, vcc, s3, v62
	s_mov_b32 s3, 0x24000
	s_nop 0
	v_addc_co_u32_e32 v35, vcc, 0, v63, vcc
	v_add_co_u32_e32 v38, vcc, s3, v62
	s_mov_b32 s3, 0x28000
	s_nop 0
	v_addc_co_u32_e32 v39, vcc, 0, v63, vcc
	global_load_dwordx4 v[34:37], v[34:35], off nt
	s_nop 0
	global_load_dwordx4 v[38:41], v[38:39], off nt
	v_add_co_u32_e32 v42, vcc, s3, v62
	s_mov_b32 s3, 0x2c000
	s_nop 0
	v_addc_co_u32_e32 v43, vcc, 0, v63, vcc
	v_add_co_u32_e32 v46, vcc, s3, v62
	s_mov_b32 s3, 0x30000
	s_nop 0
	v_addc_co_u32_e32 v47, vcc, 0, v63, vcc
	global_load_dwordx4 v[42:45], v[42:43], off nt
	s_nop 0
	global_load_dwordx4 v[46:49], v[46:47], off nt
	v_add_co_u32_e32 v50, vcc, s3, v62
	s_mov_b32 s3, 0x34000
	s_nop 0
	v_addc_co_u32_e32 v51, vcc, 0, v63, vcc
	global_load_dwordx4 v[50:53], v[50:51], off nt
	v_add_co_u32_e32 v54, vcc, s3, v62
	s_mov_b32 s3, 0x38000
	s_nop 0
	v_addc_co_u32_e32 v55, vcc, 0, v63, vcc
	global_load_dwordx4 v[54:57], v[54:55], off nt
	v_add_co_u32_e32 v58, vcc, s3, v62
	s_mov_b32 s3, 0x3c000
	s_nop 0
	v_addc_co_u32_e32 v59, vcc, 0, v63, vcc
	global_load_dwordx4 v[58:61], v[58:59], off nt
	v_add_co_u32_e32 v62, vcc, s3, v62
	s_lshl_b32 s3, s11, 1
	s_nop 0
	v_addc_co_u32_e32 v63, vcc, 0, v63, vcc
	global_load_dwordx4 v[62:65], v[62:63], off nt
	s_cselect_b32 s84, 1, 0
	s_cmp_eq_u32 s32, 1
	s_cbranch_scc1 .Lmy_yield_7
.Lmy_resume_7:
	s_cmp_lg_u32 s84, 0
	s_waitcnt vmcnt(15)
	ds_write2_b32 v69, v2, v3 offset1:1
	ds_write2_b32 v69, v4, v5 offset0:2 offset1:3
	v_add_u32_e32 v2, 0x410, v69
	s_waitcnt vmcnt(14)
	ds_write2_b32 v2, v6, v7 offset1:1
	v_add_u32_e32 v2, 0x418, v69
	ds_write2_b32 v2, v8, v9 offset1:1
	v_add_u32_e32 v2, 0x820, v69
	s_add_u32 s4, s9, s3
	s_addc_u32 s5, s10, 0
	v_lshlrev_b32_e32 v98, 1, v72
	s_waitcnt vmcnt(13)
	ds_write2_b32 v2, v10, v11 offset1:1
	v_add_u32_e32 v2, 0x828, v69
	ds_write2_b32 v2, v12, v13 offset1:1
	v_add_u32_e32 v2, 0xc30, v69
	s_waitcnt vmcnt(12)
	ds_write2_b32 v2, v14, v15 offset1:1
	v_add_u32_e32 v2, 0xc38, v69
	ds_write2_b32 v2, v16, v17 offset1:1
	v_add_u32_e32 v2, 0x1040, v69
	v_lshl_add_u64 v[8:9], s[4:5], 0, v[98:99]
	s_and_b32 s3, s15, 0x60
	s_and_b32 s4, s13, 0x300
	s_waitcnt vmcnt(11)
	ds_write2_b32 v2, v18, v19 offset1:1
	v_add_u32_e32 v2, 0x1048, v69
	ds_write2_b32 v2, v20, v21 offset1:1
	v_add_u32_e32 v2, 0x1450, v69
	s_waitcnt vmcnt(10)
	ds_write2_b32 v2, v22, v23 offset1:1
	v_add_u32_e32 v2, 0x1458, v69
	ds_write2_b32 v2, v24, v25 offset1:1
	v_add_u32_e32 v2, 0x1860, v69
	s_or_b32 s4, s4, s3
	v_add_u32_e32 v14, 0x400, v73
	v_or_b32_e32 v10, s4, v71
	s_waitcnt vmcnt(9)
	ds_write2_b32 v2, v26, v27 offset1:1
	v_add_u32_e32 v2, 0x1868, v69
	ds_write2_b32 v2, v28, v29 offset1:1
	v_add_u32_e32 v2, 0x1c70, v69
	s_waitcnt vmcnt(8)
	ds_write2_b32 v2, v30, v31 offset1:1
	v_add_u32_e32 v2, 0x1c78, v69
	ds_write2_b32 v2, v32, v33 offset1:1
	v_add_u32_e32 v2, 0x2080, v69
	v_lshlrev_b32_e32 v98, 11, v10
	v_lshl_add_u64 v[10:11], v[8:9], 0, v[98:99]
	v_or_b32_e32 v12, s4, v84
	s_waitcnt vmcnt(7)
	ds_write2_b32 v2, v34, v35 offset1:1
	v_add_u32_e32 v2, 0x2088, v69
	ds_write2_b32 v2, v36, v37 offset1:1
	v_add_u32_e32 v2, 0x2490, v69
	s_waitcnt vmcnt(6)
	ds_write2_b32 v2, v38, v39 offset1:1
	v_add_u32_e32 v2, 0x2498, v69
	ds_write2_b32 v2, v40, v41 offset1:1
	v_add_u32_e32 v2, 0x28a0, v69
	v_lshlrev_b32_e32 v98, 11, v12
	v_lshl_add_u64 v[12:13], v[8:9], 0, v[98:99]
	v_readlane_b32 s69, v253, 19
	s_waitcnt vmcnt(5)
	ds_write2_b32 v2, v42, v43 offset1:1
	v_add_u32_e32 v2, 0x28a8, v69
	ds_write2_b32 v2, v44, v45 offset1:1
	v_add_u32_e32 v2, 0x2cb0, v69
	s_waitcnt vmcnt(4)
	ds_write2_b32 v2, v46, v47 offset1:1
	v_add_u32_e32 v2, 0x2cb8, v69
	ds_write2_b32 v2, v48, v49 offset1:1
	v_add_u32_e32 v2, 0x30c0, v69
	s_waitcnt vmcnt(3)
; #define LAS __attribute__((address_space(3)))
; #define LDS_WAIT() asm volatile("s_waitcnt lgkmcnt(0)" ::: "memory")
; __device__ __forceinline__ unsigned pk2(float lo, float hi) { return pg8::cvt_pk_bf16(lo, hi); }
; __device__ __forceinline__ void xpose_item(const float* W, int K, int N, bf16* WT, const float* gain, int cmap, LAS float* scr, int item, int lane) {
;     ...
;     for (int i = 0; i < 16; ++i) { LAS float* d = scr + (4 * i + ks) * XP_STRIDE + n4; d[0] = w[i][0]; d[1] = w[i][1]; d[2] = w[i][2]; d[3] = w[i][3]; }
;     LDS_WAIT(); asm volatile("" ::: "memory");
;     int r0 = n0;
;     if (cmap == 1) { if (n0 < 1024) r0 = 2048 + n0; else if (n0 < 2048) { const int c = n0 - 1024; r0 = (c >> 7) * 256 + (c & 127); } else { const int c = n0 - 2048; r0 = (c >> 7) * 256 + 128 + (c & 127); } }
;     const int c = lane & 7;
; #pragma unroll
;     for (int j = 0; j < 8; ++j) { const int n = (lane >> 3) + 8 * j; const LAS float* sp = scr + (8 * c) * XP_STRIDE + n;
;         v4u o; o.x = pk2(sp[0 * XP_STRIDE], sp[1 * XP_STRIDE]); o.y = pk2(sp[2 * XP_STRIDE], sp[3 * XP_STRIDE]); o.z = pk2(sp[4 * XP_STRIDE], sp[5 * XP_STRIDE]); o.w = pk2(sp[6 * XP_STRIDE], sp[7 * XP_STRIDE]);
;         int rr = r0 + n;
;         if (cmap == 4) { const int cc = rr & 255; rr = (rr & ~255) + 128 * ((cc >> 5) & 1) + 32 * (cc >> 6) + (cc & 31); }
;         *(v4u*)(WT + (size_t)rr * K + k0 + 8 * c) = o; }
	ds_write2_b32 v2, v50, v51 offset1:1
	v_add_u32_e32 v2, 0x30c8, v69
	ds_write2_b32 v2, v52, v53 offset1:1
	v_add_u32_e32 v2, 0x34d0, v69
	v_readlane_b32 s70, v253, 20
	s_waitcnt vmcnt(2)
	ds_write2_b32 v2, v54, v55 offset1:1
	v_add_u32_e32 v2, 0x34d8, v69
	ds_write2_b32 v2, v56, v57 offset1:1
	v_add_u32_e32 v2, 0x38e0, v69
	v_readlane_b32 s71, v253, 21
	v_readlane_b32 s72, v253, 22
	s_waitcnt vmcnt(1)
	ds_write2_b32 v2, v58, v59 offset1:1
	v_add_u32_e32 v2, 0x38e8, v69
	ds_write2_b32 v2, v60, v61 offset1:1
	v_add_u32_e32 v2, 0x3cf0, v69
	v_readlane_b32 s73, v253, 23
	v_readlane_b32 s74, v253, 24
	s_waitcnt vmcnt(0)
	ds_write2_b32 v2, v62, v63 offset1:1
	v_add_u32_e32 v2, 0x3cf8, v69
	ds_write2_b32 v2, v64, v65 offset1:1
	s_waitcnt lgkmcnt(0)
	ds_read2_b32 v[2:3], v73 offset1:65
	s_waitcnt lgkmcnt(0)
	v_cvt_pk_bf16_f32 v2, v2, v3
	ds_read2_b32 v[4:5], v73 offset0:130 offset1:195
	s_waitcnt lgkmcnt(0)
	v_cvt_pk_bf16_f32 v3, v4, v5
	ds_read2_b32 v[4:5], v14 offset0:4 offset1:69
	s_waitcnt lgkmcnt(0)
	v_cvt_pk_bf16_f32 v4, v4, v5
	ds_read2_b32 v[6:7], v14 offset0:134 offset1:199
	s_waitcnt lgkmcnt(0)
	v_cvt_pk_bf16_f32 v5, v6, v7
	ds_read2_b32 v[6:7], v73 offset0:8 offset1:73
	global_store_dwordx4 v[10:11], v[2:5], off sc1
	v_readlane_b32 s75, v253, 25
	v_readlane_b32 s76, v253, 26
	s_waitcnt lgkmcnt(0)
	v_cvt_pk_bf16_f32 v2, v6, v7
	ds_read2_b32 v[4:5], v73 offset0:138 offset1:203
	s_waitcnt lgkmcnt(0)
	v_cvt_pk_bf16_f32 v3, v4, v5
	ds_read2_b32 v[4:5], v14 offset0:12 offset1:77
	s_waitcnt lgkmcnt(0)
	v_cvt_pk_bf16_f32 v4, v4, v5
	ds_read2_b32 v[6:7], v14 offset0:142 offset1:207
	s_waitcnt lgkmcnt(0)
	v_cvt_pk_bf16_f32 v5, v6, v7
	ds_read2_b32 v[6:7], v73 offset0:16 offset1:81
	global_store_dwordx4 v[12:13], v[2:5], off sc1
	v_or_b32_e32 v12, s4, v85
	v_lshlrev_b32_e32 v98, 11, v12
	s_waitcnt lgkmcnt(0)
	v_cvt_pk_bf16_f32 v2, v6, v7
	ds_read2_b32 v[4:5], v73 offset0:146 offset1:211
	s_waitcnt lgkmcnt(0)
	v_cvt_pk_bf16_f32 v3, v4, v5
	ds_read2_b32 v[4:5], v14 offset0:20 offset1:85
	s_waitcnt lgkmcnt(0)
	v_cvt_pk_bf16_f32 v4, v4, v5
	ds_read2_b32 v[6:7], v14 offset0:150 offset1:215
	s_waitcnt lgkmcnt(0)
	v_cvt_pk_bf16_f32 v5, v6, v7
	v_lshl_add_u64 v[12:13], v[8:9], 0, v[98:99]
	ds_read2_b32 v[6:7], v73 offset0:24 offset1:89
	global_store_dwordx4 v[12:13], v[2:5], off sc1
	v_or_b32_e32 v12, s4, v86
	v_lshlrev_b32_e32 v98, 11, v12
	s_waitcnt lgkmcnt(0)
	v_cvt_pk_bf16_f32 v2, v6, v7
	ds_read2_b32 v[4:5], v73 offset0:154 offset1:219
	s_waitcnt lgkmcnt(0)
	v_cvt_pk_bf16_f32 v3, v4, v5
	ds_read2_b32 v[4:5], v14 offset0:28 offset1:93
	s_waitcnt lgkmcnt(0)
	v_cvt_pk_bf16_f32 v4, v4, v5
	ds_read2_b32 v[6:7], v14 offset0:158 offset1:223
	s_waitcnt lgkmcnt(0)
	v_cvt_pk_bf16_f32 v5, v6, v7
	v_lshl_add_u64 v[12:13], v[8:9], 0, v[98:99]
	ds_read2_b32 v[6:7], v73 offset0:32 offset1:97
	global_store_dwordx4 v[12:13], v[2:5], off sc1
	s_mov_b32 s4, 0x40000
	v_add_co_u32_e32 v10, vcc, s4, v10
	s_waitcnt lgkmcnt(0)
	v_cvt_pk_bf16_f32 v2, v6, v7
	ds_read2_b32 v[4:5], v73 offset0:162 offset1:227
	s_waitcnt lgkmcnt(0)
	v_cvt_pk_bf16_f32 v3, v4, v5
	ds_read2_b32 v[4:5], v14 offset0:36 offset1:101
	s_waitcnt lgkmcnt(0)
	v_cvt_pk_bf16_f32 v4, v4, v5
	ds_read2_b32 v[6:7], v14 offset0:166 offset1:231
	s_waitcnt lgkmcnt(0)
	v_cvt_pk_bf16_f32 v5, v6, v7
	v_addc_co_u32_e32 v11, vcc, 0, v11, vcc
	ds_read2_b32 v[6:7], v73 offset0:40 offset1:105
	global_store_dwordx4 v[10:11], v[2:5], off sc1
	v_add_u32_e32 v12, s13, v71
	v_readlane_b32 s77, v253, 27
	s_waitcnt lgkmcnt(0)
	v_cvt_pk_bf16_f32 v2, v6, v7
	ds_read2_b32 v[4:5], v73 offset0:170 offset1:235
	s_waitcnt lgkmcnt(0)
	v_cvt_pk_bf16_f32 v3, v4, v5
	ds_read2_b32 v[4:5], v14 offset0:44 offset1:109
	s_waitcnt lgkmcnt(0)
	v_cvt_pk_bf16_f32 v4, v4, v5
	ds_read2_b32 v[6:7], v14 offset0:174 offset1:239
	s_waitcnt lgkmcnt(0)
	v_cvt_pk_bf16_f32 v5, v6, v7
	v_add_u32_e32 v6, 40, v12
	v_and_b32_e32 v6, 0x30f, v6
	v_or_b32_e32 v6, s3, v6
	v_lshlrev_b32_e32 v98, 11, v6
	v_lshl_add_u64 v[6:7], v[8:9], 0, v[98:99]
	v_add_co_u32_e32 v6, vcc, s4, v6
	ds_read2_b32 v[10:11], v73 offset0:48 offset1:113
	s_nop 0
	v_addc_co_u32_e32 v7, vcc, 0, v7, vcc
	global_store_dwordx4 v[6:7], v[2:5], off sc1
	v_readlane_b32 s80, v253, 30
	v_readlane_b32 s81, v253, 31
	s_waitcnt lgkmcnt(0)
	v_cvt_pk_bf16_f32 v2, v10, v11
	ds_read2_b32 v[4:5], v73 offset0:178 offset1:243
	s_waitcnt lgkmcnt(0)
	v_cvt_pk_bf16_f32 v3, v4, v5
	ds_read2_b32 v[4:5], v14 offset0:52 offset1:117
	s_waitcnt lgkmcnt(0)
	v_cvt_pk_bf16_f32 v4, v4, v5
	ds_read2_b32 v[6:7], v14 offset0:182 offset1:247
	s_waitcnt lgkmcnt(0)
	v_cvt_pk_bf16_f32 v5, v6, v7
	v_add_u32_e32 v6, 48, v12
	v_and_b32_e32 v6, 0x317, v6
	v_or_b32_e32 v6, s3, v6
	v_lshlrev_b32_e32 v98, 11, v6
	v_lshl_add_u64 v[6:7], v[8:9], 0, v[98:99]
	v_add_co_u32_e32 v6, vcc, s4, v6
	ds_read2_b32 v[10:11], v73 offset0:56 offset1:121
	s_nop 0
	v_addc_co_u32_e32 v7, vcc, 0, v7, vcc
	global_store_dwordx4 v[6:7], v[2:5], off sc1
	v_readlane_b32 s82, v253, 32
	v_readlane_b32 s83, v253, 33
	s_waitcnt lgkmcnt(0)
	v_cvt_pk_bf16_f32 v2, v10, v11
	ds_read2_b32 v[4:5], v73 offset0:186 offset1:251
	s_waitcnt lgkmcnt(0)
	v_cvt_pk_bf16_f32 v3, v4, v5
	ds_read2_b32 v[4:5], v14 offset0:60 offset1:125
	s_waitcnt lgkmcnt(0)
	v_cvt_pk_bf16_f32 v4, v4, v5
	ds_read2_b32 v[6:7], v14 offset0:190 offset1:255
	s_waitcnt lgkmcnt(0)
	v_cvt_pk_bf16_f32 v5, v6, v7
	v_add_u32_e32 v6, 56, v12
	v_and_b32_e32 v6, 0x31f, v6
	v_or_b32_e32 v6, s3, v6
	v_lshlrev_b32_e32 v98, 11, v6
	v_lshl_add_u64 v[6:7], v[8:9], 0, v[98:99]
	v_add_co_u32_e32 v6, vcc, 0x40000, v6
	s_nop 1
	v_addc_co_u32_e32 v7, vcc, 0, v7, vcc
	global_store_dwordx4 v[6:7], v[2:5], off sc1
	s_waitcnt lgkmcnt(0)

; __device__ __forceinline__ void xpose_item(const float* W, int K, int N, bf16* WT, const float* gain, int cmap, LAS float* scr, int item, int lane) {
;     ...
;     f32x4 w[16];
; #pragma unroll
;     for (int i = 0; i < 16; ++i) w[i] = __builtin_nontemporal_load((const f32x4*)(W + (size_t)(k0 + 4 * i + ks) * N + n0 + n4));
;     if (gain) {
; #pragma unroll
;         for (int i = 0; i < 16; ++i) w[i] = w[i] * gain[k0 + 4 * i + ks];
;     }
; __device__ __forceinline__ void prologue(const Args& a, LAS unsigned char* lds, int vcu, int G, int wave, int lane, int tid) {
;     ...
;         if (r < 2 * I_QKV) { const int l = r / I_QKV; r -= l * I_QKV; xpose_item(a.in[4] + (size_t)l * 1024 * 3072, 1024, 3072, (bf16*)(ws + WS_WQKV) + (size_t)l * 3072 * 1024, nmix + (l ? 3 : 0) * 1024, 4, scr, r, lane); continue; } r -= 2 * I_QKV;
.LBB0_561:
	s_andn2_b64 vcc, exec, s[4:5]
	s_cbranch_vccnz .LBB0_528
	s_mul_hi_i32 s2, s2, 0x2aaaaaab
	s_lshr_b32 s3, s2, 31
	s_ashr_i32 s2, s2, 7
	s_add_i32 s2, s2, s3
	s_mul_i32 s3, s2, 0xfffffd00
	s_add_i32 s3, s7, s3
	v_readlane_b32 s68, v253, 18
	s_addk_i32 s3, 0x1c40
	s_mul_i32 s5, s2, 0xc00000
	v_readlane_b32 s76, v253, 26
	s_mul_hi_i32 s4, s2, 0xc00000
	v_readlane_b32 s77, v253, 27
	s_add_u32 s11, s76, s5
	s_addc_u32 s19, s77, s4
	s_mul_hi_i32 s4, s3, 0x2aaaaaab
	s_lshr_b32 s5, s4, 31
	s_ashr_i32 s4, s4, 3
	s_add_i32 s4, s4, s5
	s_mul_i32 s5, s4, 48
	s_sub_i32 s3, s3, s5
	s_lshl_b32 s10, s4, 6
	s_lshl_b32 s4, s3, 6
	s_ashr_i32 s5, s4, 31
	s_lshl_b64 s[8:9], s[4:5], 2
	s_add_u32 s8, s11, s8
	v_or_b32_e32 v82, s10, v67
	s_addc_u32 s9, s19, s9
	v_lshlrev_b32_e32 v98, 2, v70
	v_lshl_add_u64 v[2:3], s[8:9], 0, v[98:99]
	v_or_b32_e32 v6, 4, v82
	v_mad_i64_i32 v[4:5], s[8:9], v82, s21, v[2:3]
	v_mad_i64_i32 v[6:7], s[8:9], v6, s21, v[2:3]
	global_load_dwordx4 v[62:65], v[4:5], off nt
	global_load_dwordx4 v[50:53], v[6:7], off nt
	v_or_b32_e32 v4, 8, v82
	v_or_b32_e32 v6, 12, v82
	v_mad_i64_i32 v[4:5], s[8:9], v4, s21, v[2:3]
	v_mad_i64_i32 v[6:7], s[8:9], v6, s21, v[2:3]
	global_load_dwordx4 v[58:61], v[4:5], off nt
	global_load_dwordx4 v[42:45], v[6:7], off nt
	v_or_b32_e32 v4, 16, v82
	v_or_b32_e32 v6, 20, v82
	v_mad_i64_i32 v[4:5], s[8:9], v4, s21, v[2:3]
	v_mad_i64_i32 v[6:7], s[8:9], v6, s21, v[2:3]
	global_load_dwordx4 v[54:57], v[4:5], off nt
	global_load_dwordx4 v[34:37], v[6:7], off nt
	v_or_b32_e32 v4, 24, v82
	v_or_b32_e32 v6, 28, v82
	v_mad_i64_i32 v[4:5], s[8:9], v4, s21, v[2:3]
	v_mad_i64_i32 v[6:7], s[8:9], v6, s21, v[2:3]
	global_load_dwordx4 v[46:49], v[4:5], off nt
	global_load_dwordx4 v[26:29], v[6:7], off nt
	v_or_b32_e32 v4, 32, v82
	v_or_b32_e32 v6, 36, v82
	v_mad_i64_i32 v[4:5], s[8:9], v4, s21, v[2:3]
	v_mad_i64_i32 v[6:7], s[8:9], v6, s21, v[2:3]
	global_load_dwordx4 v[38:41], v[4:5], off nt
	global_load_dwordx4 v[18:21], v[6:7], off nt
	v_or_b32_e32 v4, 40, v82
	v_or_b32_e32 v6, 44, v82
	v_mad_i64_i32 v[4:5], s[8:9], v4, s21, v[2:3]
	v_mad_i64_i32 v[6:7], s[8:9], v6, s21, v[2:3]
	global_load_dwordx4 v[30:33], v[4:5], off nt
	global_load_dwordx4 v[10:13], v[6:7], off nt
	v_or_b32_e32 v4, 48, v82
	v_or_b32_e32 v6, 52, v82
	v_mad_i64_i32 v[4:5], s[8:9], v4, s21, v[2:3]
	v_mad_i64_i32 v[6:7], s[8:9], v6, s21, v[2:3]
	global_load_dwordx4 v[22:25], v[4:5], off nt
	s_nop 0
	global_load_dwordx4 v[6:9], v[6:7], off nt
	v_or_b32_e32 v4, 56, v82
	v_or_b32_e32 v14, 60, v82
	v_mad_i64_i32 v[4:5], s[8:9], v4, s21, v[2:3]
	v_mad_i64_i32 v[2:3], s[8:9], v14, s21, v[2:3]
	global_load_dwordx4 v[14:17], v[4:5], off nt
	s_nop 0
	global_load_dwordx4 v[2:5], v[2:3], off nt
	v_readlane_b32 s8, v253, 34
	v_readlane_b32 s9, v253, 35
	v_readlane_b32 s72, v253, 22
	v_readlane_b32 s73, v253, 23
	s_andn2_b64 vcc, exec, s[8:9]
	v_readlane_b32 s69, v253, 19
	v_readlane_b32 s70, v253, 20
	v_readlane_b32 s71, v253, 21
	v_readlane_b32 s74, v253, 24
	v_readlane_b32 s75, v253, 25
	v_readlane_b32 s78, v253, 28
	v_readlane_b32 s79, v253, 29
	v_readlane_b32 s80, v253, 30
	v_readlane_b32 s81, v253, 31
	v_readlane_b32 s82, v253, 32
	v_readlane_b32 s83, v253, 33
	s_cbranch_vccnz .LBB0_527
	s_add_i32 s3, s7, 0x1f3f
	s_cmpk_lt_u32 s3, 0x5ff
	s_cselect_b32 s3, 0, 0x3000
	s_add_u32 s8, s72, s3
	v_ashrrev_i32_e32 v83, 31, v82
	s_addc_u32 s9, s73, 0
	v_lshl_add_u64 v[82:83], v[82:83], 2, s[8:9]
	global_load_dword v94, v[82:83], off
	global_load_dword v96, v[82:83], off offset:16
	global_load_dword v98, v[82:83], off offset:32
	global_load_dword v100, v[82:83], off offset:48
	global_load_dword v102, v[82:83], off offset:64
	global_load_dword v104, v[82:83], off offset:80
	global_load_dword v106, v[82:83], off offset:96
	global_load_dword v108, v[82:83], off offset:112
	global_load_dword v110, v[82:83], off offset:128
	global_load_dword v112, v[82:83], off offset:144
	global_load_dword v114, v[82:83], off offset:160
	global_load_dword v116, v[82:83], off offset:176
	global_load_dword v118, v[82:83], off offset:192
	global_load_dword v120, v[82:83], off offset:208
	global_load_dword v122, v[82:83], off offset:224
	s_nop 0
	global_load_dword v82, v[82:83], off offset:240
	s_cselect_b32 s84, 1, 0
	s_cmp_eq_u32 s32, 1
	s_cbranch_scc1 .Lmy_yield_8
.Lmy_resume_8:
	s_cmp_lg_u32 s84, 0
	s_waitcnt vmcnt(15)
	v_pk_mul_f32 v[64:65], v[64:65], v[94:95] op_sel_hi:[1,0]
	v_pk_mul_f32 v[62:63], v[62:63], v[94:95] op_sel_hi:[1,0]
	s_waitcnt vmcnt(14)
	v_pk_mul_f32 v[52:53], v[52:53], v[96:97] op_sel_hi:[1,0]
	v_pk_mul_f32 v[50:51], v[50:51], v[96:97] op_sel_hi:[1,0]
	s_waitcnt vmcnt(13)
	v_pk_mul_f32 v[60:61], v[60:61], v[98:99] op_sel_hi:[1,0]
	v_pk_mul_f32 v[58:59], v[58:59], v[98:99] op_sel_hi:[1,0]
	s_waitcnt vmcnt(12)
	v_pk_mul_f32 v[44:45], v[44:45], v[100:101] op_sel_hi:[1,0]
	v_pk_mul_f32 v[42:43], v[42:43], v[100:101] op_sel_hi:[1,0]
	s_waitcnt vmcnt(11)
	v_pk_mul_f32 v[56:57], v[56:57], v[102:103] op_sel_hi:[1,0]
	v_pk_mul_f32 v[54:55], v[54:55], v[102:103] op_sel_hi:[1,0]
	s_waitcnt vmcnt(10)
	v_pk_mul_f32 v[36:37], v[36:37], v[104:105] op_sel_hi:[1,0]
	v_pk_mul_f32 v[34:35], v[34:35], v[104:105] op_sel_hi:[1,0]
	s_waitcnt vmcnt(9)
	v_pk_mul_f32 v[48:49], v[48:49], v[106:107] op_sel_hi:[1,0]
	v_pk_mul_f32 v[46:47], v[46:47], v[106:107] op_sel_hi:[1,0]
	s_waitcnt vmcnt(8)
	v_pk_mul_f32 v[28:29], v[28:29], v[108:109] op_sel_hi:[1,0]
	v_pk_mul_f32 v[26:27], v[26:27], v[108:109] op_sel_hi:[1,0]
	s_waitcnt vmcnt(7)
	v_pk_mul_f32 v[40:41], v[40:41], v[110:111] op_sel_hi:[1,0]
	v_pk_mul_f32 v[38:39], v[38:39], v[110:111] op_sel_hi:[1,0]
	s_waitcnt vmcnt(6)
	v_pk_mul_f32 v[20:21], v[20:21], v[112:113] op_sel_hi:[1,0]
	v_pk_mul_f32 v[18:19], v[18:19], v[112:113] op_sel_hi:[1,0]
	s_waitcnt vmcnt(5)
	v_pk_mul_f32 v[32:33], v[32:33], v[114:115] op_sel_hi:[1,0]
	v_pk_mul_f32 v[30:31], v[30:31], v[114:115] op_sel_hi:[1,0]
	s_waitcnt vmcnt(4)
	v_pk_mul_f32 v[12:13], v[12:13], v[116:117] op_sel_hi:[1,0]
	v_pk_mul_f32 v[10:11], v[10:11], v[116:117] op_sel_hi:[1,0]
	s_waitcnt vmcnt(3)
	v_pk_mul_f32 v[24:25], v[24:25], v[118:119] op_sel_hi:[1,0]
	v_pk_mul_f32 v[22:23], v[22:23], v[118:119] op_sel_hi:[1,0]
	s_waitcnt vmcnt(2)
	v_pk_mul_f32 v[8:9], v[8:9], v[120:121] op_sel_hi:[1,0]
	v_pk_mul_f32 v[6:7], v[6:7], v[120:121] op_sel_hi:[1,0]
	s_waitcnt vmcnt(1)
	v_pk_mul_f32 v[16:17], v[16:17], v[122:123] op_sel_hi:[1,0]
	v_pk_mul_f32 v[14:15], v[14:15], v[122:123] op_sel_hi:[1,0]
	s_waitcnt vmcnt(0)
	v_pk_mul_f32 v[4:5], v[4:5], v[82:83] op_sel_hi:[1,0]
	v_pk_mul_f32 v[2:3], v[2:3], v[82:83] op_sel_hi:[1,0]
	s_branch .LBB0_527

; __device__ __forceinline__ void xcd_barrier(const XcdBarrier& b) {
;     asm volatile("s_waitcnt vmcnt(0)" ::: "memory");
;     __syncthreads();
;     if (threadIdx.x == 0) {
; __device__ __forceinline__ void prologue(const Args& a, LAS unsigned char* lds, int vcu, int G, int wave, int lane, int tid) {
;     ...
;     for (int it = gw; it < NITEMS; it += NGW) {
.LBB0_585:
	v_readfirstlane_b32 s3, v0
	s_lshr_b32 s3, s3, 6
	s_cmp_eq_u32 s3, 0
	s_cbranch_scc1 .Lmy_std
	s_cmp_gt_u32 s3, 3
	s_cbranch_scc0 .Lmy_items

; #define LAS __attribute__((address_space(3)))
; __device__ __forceinline__ void xcd_barrier(const XcdBarrier& b) {
;     asm volatile("s_waitcnt vmcnt(0)" ::: "memory");
;     __syncthreads();
;     if (threadIdx.x == 0) {
;         unsigned* bar = b.bar;
;         __builtin_amdgcn_s_waitcnt(0);
;         unsigned nloc = b.st[0], nx = b.st[1];
;         if (nloc == 0u) { xcd_barrier_complete(bar, b.x, nloc, nx); b.st[0] = nloc; b.st[1] = nx; }
;         const unsigned old = xb_add(&bar[XB_XSUB(b.x)], 1u);
;         const unsigned gen = old / nloc;
;         if (old + 1u == (gen + 1u) * nloc) {
;             __builtin_amdgcn_fence(__ATOMIC_RELEASE, "agent");
;             asm volatile("s_waitcnt vmcnt(0)" ::: "memory");
;             const unsigned og = xb_add(&bar[XB_TOP], 1u);
;             const unsigned tg = og / nx;
;             if (og + 1u == (tg + 1u) * nx) xb_add(&bar[XB_TOPGEN], 1u);
;             else XB_SPIN(xb_ld(&bar[XB_TOPGEN]) == tg, bar);
;             __builtin_amdgcn_fence(__ATOMIC_ACQUIRE, "agent");
;             xb_add(&bar[XB_XGEN(b.x)], 1u);
;             asm volatile("s_waitcnt vmcnt(0)" ::: "memory");
;         } else {
;             XB_SPIN(xb_ld(&bar[XB_XGEN(b.x)]) == gen, bar);
;             __builtin_amdgcn_fence(__ATOMIC_ACQUIRE, "agent");
;             asm volatile("s_waitcnt vmcnt(0)" ::: "memory");
;         }
;     }
;     __syncthreads();
; __device__ __forceinline__ void prologue(const Args& a, LAS unsigned char* lds, int vcu, int G, int wave, int lane, int tid) {
;     unsigned char* ws = a.ws;
;     LAS float* scr = (LAS float*)(lds + wave * XP_WAVE_BYTES);
;     const int gw = vcu * NWAVES + wave, NGW = G * NWAVES;
;     constexpr int I_QKV = 16 * 48, I_SQ = 16 * 16, I_POOL = 4 * 4, I_UP = 16 * 64, I_DN = 64 * 16;
;     constexpr int NITEMS = 2 * I_QKV + 2 * I_SQ + 4 * I_POOL + I_QKV + I_SQ + 4 * I_UP + 4 * I_DN;
;     const float* nmix = a.in[2]; const float* nmlp = a.in[3];
;     for (int it = gw; it < NITEMS; it += NGW) {
;         int r = it;
;         if (r < 2 * I_QKV) { const int l = r / I_QKV; r -= l * I_QKV; xpose_item(a.in[4] + (size_t)l * 1024 * 3072, 1024, 3072, (bf16*)(ws + WS_WQKV) + (size_t)l * 3072 * 1024, nmix + (l ? 3 : 0) * 1024, 4, scr, r, lane); continue; } r -= 2 * I_QKV;
.Lmy_items:
	s_mov_b64 exec, -1
	v_writelane_b32 v200, s0, 0
	v_writelane_b32 v200, s1, 1
	v_writelane_b32 v200, s2, 2
	v_writelane_b32 v200, s3, 3
	v_writelane_b32 v200, s4, 4
	v_writelane_b32 v200, s5, 5
	v_writelane_b32 v200, s6, 6
	v_writelane_b32 v200, s7, 7
	v_writelane_b32 v200, s8, 8
	v_writelane_b32 v200, s9, 9
	v_writelane_b32 v200, s10, 10
	v_writelane_b32 v200, s11, 11
	v_writelane_b32 v200, s12, 12
	v_writelane_b32 v200, s13, 13
	v_writelane_b32 v200, s14, 14
	v_writelane_b32 v200, s15, 15
	v_writelane_b32 v200, s16, 16
	v_writelane_b32 v200, s17, 17
	v_writelane_b32 v200, s18, 18
	v_writelane_b32 v200, s19, 19
	v_writelane_b32 v200, s68, 20
	v_writelane_b32 v200, s69, 21
	v_writelane_b32 v200, s70, 22
	v_writelane_b32 v200, s71, 23
	v_writelane_b32 v200, s72, 24
	v_writelane_b32 v200, s73, 25
	v_writelane_b32 v200, s74, 26
	v_writelane_b32 v200, s75, 27
	v_writelane_b32 v200, s76, 28
	v_writelane_b32 v200, s77, 29
	v_writelane_b32 v200, s78, 30
	v_writelane_b32 v200, s79, 31
	v_writelane_b32 v200, s80, 32
	v_writelane_b32 v200, s81, 33
	v_writelane_b32 v200, s82, 34
	v_writelane_b32 v200, s83, 35
	v_writelane_b32 v200, s86, 36
	s_add_i32 s2, s66, -1
	s_add_i32 s4, s66, -2
	s_cmp_gt_u32 s66, 8
	s_cselect_b32 s2, s4, s2
	s_add_i32 s5, s3, -1
	s_lshl_b32 s5, s5, 8
	v_readlane_b32 s6, v255, 47
	s_lshr_b32 s7, s6, 3
	s_add_i32 s5, s5, s7
	s_cmp_ge_u32 s5, 640
	s_cbranch_scc1 .Lmy_items_none
	s_mul_i32 s2, s2, 640
	s_add_i32 s2, s2, s5
	s_cmp_ge_u32 s2, 10560
	s_cbranch_scc1 .Lmy_items_none
	s_mov_b32 s4, 1536
	s_cmp_ge_u32 s2, 256
	s_cselect_b32 s4, 2880, s4
	s_cmp_ge_u32 s2, 1280
	s_cselect_b32 s4, 5952, s4
	s_cmp_ge_u32 s2, 2304
	s_cselect_b32 s4, -256, s4
	s_cmp_ge_u32 s2, 2368
	s_cselect_b32 s4, 1792, s4
	s_cmp_ge_u32 s2, 3392
	s_cselect_b32 s4, 4864, s4
	s_cmp_ge_u32 s2, 4416
	s_cselect_b32 s4, -2304, s4
	s_cmp_ge_u32 s2, 5184
	s_cselect_b32 s4, -2304, s4
	s_cmp_ge_u32 s2, 5440
	s_cselect_b32 s4, -256, s4
	s_cmp_ge_u32 s2, 6464
	s_cselect_b32 s4, 2816, s4
	s_cmp_ge_u32 s2, 7488
	s_cselect_b32 s4, -6720, s4
	s_cmp_ge_u32 s2, 8256
	s_cselect_b32 s4, -6464, s4
	s_cmp_ge_u32 s2, 8512
	s_cselect_b32 s4, -2304, s4
	s_cmp_ge_u32 s2, 9536
	s_cselect_b32 s4, 768, s4
	s_add_i32 s19, s2, s4
	v_mov_b32_e32 v221, v0
	v_readlane_b32 s65, v253, 2
	s_mov_b32 s70, s3
	s_mov_b32 s85, s6
	v_readlane_b32 s28, v255, 48
	s_add_i32 s0, s70, s85
	s_sub_i32 s19, s19, s0
	s_lshl_b32 s12, s65, 3
	v_and_b32_e32 v2, 63, v221
	v_lshlrev_b32_e32 v66, 2, v2
	v_lshlrev_b32_e32 v68, 3, v2
	s_mov_b32 s32, 1
	s_branch .Lmy_p0_init
.Lmy_yield_0:
	s_mov_b32 s32, 2
	s_branch .Lmy_yield
.Lmy_yield_1:
	s_mov_b32 s32, 3
	s_branch .Lmy_yield
.Lmy_yield_2:
	s_mov_b32 s32, 4
	s_branch .Lmy_yield
.Lmy_yield_3:
	s_mov_b32 s32, 5
	s_branch .Lmy_yield
.Lmy_yield_4:
	s_mov_b32 s32, 6
	s_branch .Lmy_yield
.Lmy_yield_5:
	s_mov_b32 s32, 7
	s_branch .Lmy_yield
.Lmy_yield_6:
	s_mov_b32 s32, 8
	s_branch .Lmy_yield
.Lmy_yield_7:
	s_mov_b32 s32, 9
	s_branch .Lmy_yield
.Lmy_yield_8:
	s_mov_b32 s32, 10
	s_branch .Lmy_yield
.Lmy_yield:
	s_waitcnt vmcnt(16)
	s_waitcnt lgkmcnt(0)
	s_barrier
	s_cmp_eq_u32 s32, 2
	s_cbranch_scc1 .Lmy_resume_0
	s_cmp_eq_u32 s32, 3
	s_cbranch_scc1 .Lmy_resume_1
	s_cmp_eq_u32 s32, 4
	s_cbranch_scc1 .Lmy_resume_2
	s_cmp_eq_u32 s32, 5
	s_cbranch_scc1 .Lmy_resume_3
	s_cmp_eq_u32 s32, 6
	s_cbranch_scc1 .Lmy_resume_4
	s_cmp_eq_u32 s32, 7
	s_cbranch_scc1 .Lmy_resume_5
	s_cmp_eq_u32 s32, 8
	s_cbranch_scc1 .Lmy_resume_6
	s_cmp_eq_u32 s32, 9
	s_cbranch_scc1 .Lmy_resume_7
	s_cmp_eq_u32 s32, 10
	s_cbranch_scc1 .Lmy_resume_8
	s_endpgm
.Lmy_p0_ret:
	s_cmp_lg_u32 s32, 1
	s_cbranch_scc1 .Lmy_p0_ret2
	s_waitcnt vmcnt(0)
	s_waitcnt lgkmcnt(0)
	s_barrier
.Lmy_p0_ret2:
	v_readlane_b32 s0, v200, 0
	v_readlane_b32 s1, v200, 1
	v_readlane_b32 s2, v200, 2
	v_readlane_b32 s3, v200, 3
	v_readlane_b32 s4, v200, 4
	v_readlane_b32 s5, v200, 5
	v_readlane_b32 s6, v200, 6
	v_readlane_b32 s7, v200, 7
	v_readlane_b32 s8, v200, 8
	v_readlane_b32 s9, v200, 9
	v_readlane_b32 s10, v200, 10
	v_readlane_b32 s11, v200, 11
	v_readlane_b32 s12, v200, 12
	v_readlane_b32 s13, v200, 13
	v_readlane_b32 s14, v200, 14
	v_readlane_b32 s15, v200, 15
	v_readlane_b32 s16, v200, 16
	v_readlane_b32 s17, v200, 17
	v_readlane_b32 s18, v200, 18
	v_readlane_b32 s19, v200, 19
	v_readlane_b32 s68, v200, 20
	v_readlane_b32 s69, v200, 21
	v_readlane_b32 s70, v200, 22
	v_readlane_b32 s71, v200, 23
	v_readlane_b32 s72, v200, 24
	v_readlane_b32 s73, v200, 25
	v_readlane_b32 s74, v200, 26
	v_readlane_b32 s75, v200, 27
	v_readlane_b32 s76, v200, 28
	v_readlane_b32 s77, v200, 29
	v_readlane_b32 s78, v200, 30
	v_readlane_b32 s79, v200, 31
	v_readlane_b32 s80, v200, 32
	v_readlane_b32 s81, v200, 33
	v_readlane_b32 s82, v200, 34
	v_readlane_b32 s83, v200, 35
	v_readlane_b32 s86, v200, 36
	s_mov_b32 s32, 0
	s_branch .LBB0_633
